# c2 plus s_nop padding in the load stages so every MFMA block starts on a 64-byte boundary (all seven K-loops)
# speedup vs baseline: 1.0017x; 1.0016x over previous
.LBB0_256:
	v_add_u32_e32 v172, s70, v160
	v_add_u32_e32 v188, s71, v160
	ds_read_b128 v[154:157], v172
	ds_read_b128 v[164:167], v172 offset:1024
	ds_read_b128 v[168:171], v172 offset:2048
	ds_read_b128 v[172:175], v172 offset:3072
	ds_read_b128 v[176:179], v188
	ds_read_b128 v[180:183], v188 offset:1024
	ds_read_b128 v[184:187], v188 offset:2048
	ds_read_b128 v[188:191], v188 offset:3072
	s_add_i32 s75, s30, 2
	s_add_u32 s31, s28, 0xfffc0080
	s_addc_u32 s34, s29, -1
	s_cmp_eq_u32 s67, s30
	s_cselect_b32 s30, s26, s17
	s_cselect_b32 s35, s25, s34
	s_cselect_b32 s34, s24, s31
	s_cselect_b32 s31, s27, s19
	v_lshl_add_u64 v[224:225], s[28:29], 0, v[146:147]
	s_add_i32 m0, s58, 0xc000
	ds_read_b128 v[192:195], v163
	ds_read_b128 v[196:199], v163 offset:1024
	ds_read_b128 v[200:203], v163 offset:2048
	ds_read_b128 v[204:207], v163 offset:3072
	ds_read_b128 v[208:211], v163 offset:4096
	ds_read_b128 v[212:215], v163 offset:5120
	ds_read_b128 v[216:219], v163 offset:6144
	ds_read_b128 v[220:223], v163 offset:7168
	global_load_lds_dwordx4 v[224:225], off
	v_lshl_add_u64 v[224:225], s[28:29], 0, v[148:149]
	s_add_i32 m0, s58, 0xe000
	s_nop 0
	global_load_lds_dwordx4 v[224:225], off
	s_nop 0
	s_nop 0
	s_nop 0
	s_nop 0
	s_nop 0
	s_nop 0
	s_waitcnt vmcnt(8)
	s_waitcnt lgkmcnt(0)
	s_barrier
	v_mfma_f32_16x16x32_bf16 v[42:45], v[154:157], v[192:195], v[42:45]
	v_mfma_f32_16x16x32_bf16 v[26:29], v[168:171], v[192:195], v[26:29]
	v_mfma_f32_16x16x32_bf16 v[54:57], v[154:157], v[200:203], v[54:57]
	v_mfma_f32_16x16x32_bf16 v[38:41], v[168:171], v[200:203], v[38:41]
	v_mfma_f32_16x16x32_bf16 v[66:69], v[154:157], v[208:211], v[66:69]
	v_mfma_f32_16x16x32_bf16 v[50:53], v[168:171], v[208:211], v[50:53]
	v_mfma_f32_16x16x32_bf16 v[62:65], v[154:157], v[216:219], v[62:65]
	v_mfma_f32_16x16x32_bf16 v[46:49], v[168:171], v[216:219], v[46:49]
	v_mfma_f32_16x16x32_bf16 v[42:45], v[164:167], v[196:199], v[42:45]
	v_mfma_f32_16x16x32_bf16 v[26:29], v[172:175], v[196:199], v[26:29]
	v_mfma_f32_16x16x32_bf16 v[54:57], v[164:167], v[204:207], v[54:57]
	v_mfma_f32_16x16x32_bf16 v[38:41], v[172:175], v[204:207], v[38:41]
	v_mfma_f32_16x16x32_bf16 v[66:69], v[164:167], v[212:215], v[66:69]
	v_mfma_f32_16x16x32_bf16 v[50:53], v[172:175], v[212:215], v[50:53]
	v_mfma_f32_16x16x32_bf16 v[62:65], v[164:167], v[220:223], v[62:65]
	v_mfma_f32_16x16x32_bf16 v[46:49], v[172:175], v[220:223], v[46:49]
	v_mfma_f32_16x16x32_bf16 v[14:17], v[176:179], v[192:195], v[14:17]
	v_mfma_f32_16x16x32_bf16 v[2:5], v[184:187], v[192:195], v[2:5]
	v_mfma_f32_16x16x32_bf16 v[22:25], v[176:179], v[200:203], v[22:25]
	v_mfma_f32_16x16x32_bf16 v[6:9], v[184:187], v[200:203], v[6:9]
	v_mfma_f32_16x16x32_bf16 v[30:33], v[176:179], v[208:211], v[30:33]
	v_mfma_f32_16x16x32_bf16 v[10:13], v[184:187], v[208:211], v[10:13]
	v_mfma_f32_16x16x32_bf16 v[34:37], v[176:179], v[216:219], v[34:37]
	v_mfma_f32_16x16x32_bf16 v[18:21], v[184:187], v[216:219], v[18:21]
	v_mfma_f32_16x16x32_bf16 v[14:17], v[180:183], v[196:199], v[14:17]
	v_mfma_f32_16x16x32_bf16 v[2:5], v[188:191], v[196:199], v[2:5]
	v_mfma_f32_16x16x32_bf16 v[22:25], v[180:183], v[204:207], v[22:25]
	v_mfma_f32_16x16x32_bf16 v[6:9], v[188:191], v[204:207], v[6:9]
	v_mfma_f32_16x16x32_bf16 v[30:33], v[180:183], v[212:215], v[30:33]
	v_mfma_f32_16x16x32_bf16 v[10:13], v[188:191], v[212:215], v[10:13]
	v_mfma_f32_16x16x32_bf16 v[34:37], v[180:183], v[220:223], v[34:37]
	v_mfma_f32_16x16x32_bf16 v[18:21], v[188:191], v[220:223], v[18:21]
	s_barrier
	s_add_i32 s50, s70, s54
	v_lshl_add_u64 v[224:225], s[30:31], 0, v[134:135]
	s_mov_b32 m0, s50
	ds_read_b128 v[192:195], v163 offset:16384
	ds_read_b128 v[196:199], v163 offset:17408
	ds_read_b128 v[200:203], v163 offset:18432
	ds_read_b128 v[204:207], v163 offset:19456
	ds_read_b128 v[208:211], v163 offset:20480
	ds_read_b128 v[212:215], v163 offset:21504
	ds_read_b128 v[216:219], v163 offset:22528
	ds_read_b128 v[220:223], v163 offset:23552
	global_load_lds_dwordx4 v[224:225], off
	s_add_i32 m0, s50, 0x2000
	s_add_u32 s76, s30, 0x40000
	v_lshl_add_u64 v[226:227], s[30:31], 0, v[130:131]
	s_addc_u32 s77, s31, 0
	s_add_i32 s50, s71, s54
	global_load_lds_dwordx4 v[226:227], off
	v_lshl_add_u64 v[228:229], s[76:77], 0, v[134:135]
	s_mov_b32 m0, s50
	v_lshl_add_u64 v[230:231], s[34:35], 0, v[132:133]
	global_load_lds_dwordx4 v[228:229], off
	v_lshl_add_u64 v[228:229], s[76:77], 0, v[130:131]
	s_add_i32 m0, s50, 0x2000
	s_nop 0
	global_load_lds_dwordx4 v[228:229], off
	v_lshl_add_u64 v[228:229], s[34:35], 0, v[136:137]
	s_mov_b32 m0, s58
	s_nop 0
	global_load_lds_dwordx4 v[228:229], off
	s_mov_b32 m0, s59
	s_nop 0
	global_load_lds_dwordx4 v[230:231], off
	s_nop 0
	s_nop 0
	s_nop 0
	s_nop 0
	s_waitcnt vmcnt(8)
	s_waitcnt lgkmcnt(0)
	s_barrier
	v_mfma_f32_16x16x32_bf16 v[110:113], v[154:157], v[192:195], v[110:113]
	v_mfma_f32_16x16x32_bf16 v[86:89], v[168:171], v[192:195], v[86:89]
	v_mfma_f32_16x16x32_bf16 v[106:109], v[154:157], v[200:203], v[106:109]
	v_mfma_f32_16x16x32_bf16 v[82:85], v[168:171], v[200:203], v[82:85]
	v_mfma_f32_16x16x32_bf16 v[118:121], v[154:157], v[208:211], v[118:121]
	v_mfma_f32_16x16x32_bf16 v[94:97], v[168:171], v[208:211], v[94:97]
	v_mfma_f32_16x16x32_bf16 v[126:129], v[154:157], v[216:219], v[126:129]
	v_mfma_f32_16x16x32_bf16 v[102:105], v[168:171], v[216:219], v[102:105]
	v_mfma_f32_16x16x32_bf16 v[110:113], v[164:167], v[196:199], v[110:113]
	v_mfma_f32_16x16x32_bf16 v[86:89], v[172:175], v[196:199], v[86:89]
	v_mfma_f32_16x16x32_bf16 v[106:109], v[164:167], v[204:207], v[106:109]
	v_mfma_f32_16x16x32_bf16 v[82:85], v[172:175], v[204:207], v[82:85]
	v_mfma_f32_16x16x32_bf16 v[118:121], v[164:167], v[212:215], v[118:121]
	v_mfma_f32_16x16x32_bf16 v[94:97], v[172:175], v[212:215], v[94:97]
	v_mfma_f32_16x16x32_bf16 v[126:129], v[164:167], v[220:223], v[126:129]
	v_mfma_f32_16x16x32_bf16 v[102:105], v[172:175], v[220:223], v[102:105]
	v_mfma_f32_16x16x32_bf16 v[70:73], v[176:179], v[192:195], v[70:73]
	v_mfma_f32_16x16x32_bf16 v[58:61], v[184:187], v[192:195], v[58:61]
	v_mfma_f32_16x16x32_bf16 v[74:77], v[176:179], v[200:203], v[74:77]
	v_mfma_f32_16x16x32_bf16 v[78:81], v[184:187], v[200:203], v[78:81]
	v_mfma_f32_16x16x32_bf16 v[114:117], v[176:179], v[208:211], v[114:117]
	v_mfma_f32_16x16x32_bf16 v[90:93], v[184:187], v[208:211], v[90:93]
	v_mfma_f32_16x16x32_bf16 v[122:125], v[176:179], v[216:219], v[122:125]
	v_mfma_f32_16x16x32_bf16 v[98:101], v[184:187], v[216:219], v[98:101]
	v_mfma_f32_16x16x32_bf16 v[70:73], v[180:183], v[196:199], v[70:73]
	v_mfma_f32_16x16x32_bf16 v[58:61], v[188:191], v[196:199], v[58:61]
	v_mfma_f32_16x16x32_bf16 v[74:77], v[180:183], v[204:207], v[74:77]
	v_mfma_f32_16x16x32_bf16 v[78:81], v[188:191], v[204:207], v[78:81]
	v_mfma_f32_16x16x32_bf16 v[114:117], v[180:183], v[212:215], v[114:117]
	v_mfma_f32_16x16x32_bf16 v[90:93], v[188:191], v[212:215], v[90:93]
	v_mfma_f32_16x16x32_bf16 v[122:125], v[180:183], v[220:223], v[122:125]
	v_mfma_f32_16x16x32_bf16 v[98:101], v[188:191], v[220:223], v[98:101]
	s_barrier
	s_add_i32 s50, 0, 0x18000
	s_add_i32 s51, 0, 0x1c000
	v_add_u32_e32 v172, s50, v160
	v_add_u32_e32 v188, s51, v160
	ds_read_b128 v[154:157], v172
	ds_read_b128 v[164:167], v172 offset:1024
	ds_read_b128 v[168:171], v172 offset:2048
	ds_read_b128 v[172:175], v172 offset:3072
	ds_read_b128 v[176:179], v188
	ds_read_b128 v[180:183], v188 offset:1024
	ds_read_b128 v[184:187], v188 offset:2048
	ds_read_b128 v[188:191], v188 offset:3072
	s_add_u32 s34, s34, 0x40000
	s_addc_u32 s35, s35, 0
	s_mov_b32 m0, s60
	v_lshl_add_u64 v[232:233], s[34:35], 0, v[136:137]
	ds_read_b128 v[192:195], v163 offset:32768
	ds_read_b128 v[196:199], v163 offset:33792
	ds_read_b128 v[200:203], v163 offset:34816
	ds_read_b128 v[204:207], v163 offset:35840
	ds_read_b128 v[208:211], v163 offset:36864
	ds_read_b128 v[212:215], v163 offset:37888
	ds_read_b128 v[216:219], v163 offset:38912
	ds_read_b128 v[220:223], v163 offset:39936
	global_load_lds_dwordx4 v[232:233], off
	v_lshl_add_u64 v[232:233], s[34:35], 0, v[132:133]
	s_mov_b32 m0, s61
	s_nop 0
	global_load_lds_dwordx4 v[232:233], off
	s_nop 0
	s_nop 0
	s_nop 0
	s_nop 0
	s_nop 0
	s_nop 0
	s_nop 0
	s_nop 0
	s_waitcnt vmcnt(8)
	s_waitcnt lgkmcnt(0)
	s_barrier
	v_mfma_f32_16x16x32_bf16 v[42:45], v[154:157], v[192:195], v[42:45]
	v_mfma_f32_16x16x32_bf16 v[26:29], v[168:171], v[192:195], v[26:29]
	v_mfma_f32_16x16x32_bf16 v[54:57], v[154:157], v[200:203], v[54:57]
	v_mfma_f32_16x16x32_bf16 v[38:41], v[168:171], v[200:203], v[38:41]
	v_mfma_f32_16x16x32_bf16 v[66:69], v[154:157], v[208:211], v[66:69]
	v_mfma_f32_16x16x32_bf16 v[50:53], v[168:171], v[208:211], v[50:53]
	v_mfma_f32_16x16x32_bf16 v[62:65], v[154:157], v[216:219], v[62:65]
	v_mfma_f32_16x16x32_bf16 v[46:49], v[168:171], v[216:219], v[46:49]
	v_mfma_f32_16x16x32_bf16 v[42:45], v[164:167], v[196:199], v[42:45]
	v_mfma_f32_16x16x32_bf16 v[26:29], v[172:175], v[196:199], v[26:29]
	v_mfma_f32_16x16x32_bf16 v[54:57], v[164:167], v[204:207], v[54:57]
	v_mfma_f32_16x16x32_bf16 v[38:41], v[172:175], v[204:207], v[38:41]
	v_mfma_f32_16x16x32_bf16 v[66:69], v[164:167], v[212:215], v[66:69]
	v_mfma_f32_16x16x32_bf16 v[50:53], v[172:175], v[212:215], v[50:53]
	v_mfma_f32_16x16x32_bf16 v[62:65], v[164:167], v[220:223], v[62:65]
	v_mfma_f32_16x16x32_bf16 v[46:49], v[172:175], v[220:223], v[46:49]
	v_mfma_f32_16x16x32_bf16 v[14:17], v[176:179], v[192:195], v[14:17]
	v_mfma_f32_16x16x32_bf16 v[2:5], v[184:187], v[192:195], v[2:5]
	v_mfma_f32_16x16x32_bf16 v[22:25], v[176:179], v[200:203], v[22:25]
	v_mfma_f32_16x16x32_bf16 v[6:9], v[184:187], v[200:203], v[6:9]
	v_mfma_f32_16x16x32_bf16 v[30:33], v[176:179], v[208:211], v[30:33]
	v_mfma_f32_16x16x32_bf16 v[10:13], v[184:187], v[208:211], v[10:13]
	v_mfma_f32_16x16x32_bf16 v[34:37], v[176:179], v[216:219], v[34:37]
	v_mfma_f32_16x16x32_bf16 v[18:21], v[184:187], v[216:219], v[18:21]
	v_mfma_f32_16x16x32_bf16 v[14:17], v[180:183], v[196:199], v[14:17]
	v_mfma_f32_16x16x32_bf16 v[2:5], v[188:191], v[196:199], v[2:5]
	v_mfma_f32_16x16x32_bf16 v[22:25], v[180:183], v[204:207], v[22:25]
	v_mfma_f32_16x16x32_bf16 v[6:9], v[188:191], v[204:207], v[6:9]
	v_mfma_f32_16x16x32_bf16 v[30:33], v[180:183], v[212:215], v[30:33]
	v_mfma_f32_16x16x32_bf16 v[10:13], v[188:191], v[212:215], v[10:13]
	v_mfma_f32_16x16x32_bf16 v[34:37], v[180:183], v[220:223], v[34:37]
	v_mfma_f32_16x16x32_bf16 v[18:21], v[188:191], v[220:223], v[18:21]
	s_barrier
	s_add_i32 s34, s50, s54
	v_lshl_add_u64 v[224:225], v[224:225], 0, s[10:11]
	s_mov_b32 m0, s34
	ds_read_b128 v[192:195], v163 offset:49152
	ds_read_b128 v[196:199], v163 offset:50176
	ds_read_b128 v[200:203], v163 offset:51200
	ds_read_b128 v[204:207], v163 offset:52224
	ds_read_b128 v[208:211], v163 offset:53248
	ds_read_b128 v[212:215], v163 offset:54272
	ds_read_b128 v[216:219], v163 offset:55296
	ds_read_b128 v[220:223], v163 offset:56320
	global_load_lds_dwordx4 v[224:225], off
	s_add_i32 m0, s34, 0x2000
	s_add_u32 s30, s30, 0x40080
	v_lshl_add_u64 v[224:225], v[226:227], 0, s[10:11]
	s_addc_u32 s31, s31, 0
	s_add_i32 s34, s51, s54
	global_load_lds_dwordx4 v[224:225], off
	v_lshl_add_u64 v[224:225], s[30:31], 0, v[134:135]
	s_mov_b32 m0, s34
	s_nop 0
	global_load_lds_dwordx4 v[224:225], off
	v_lshl_add_u64 v[224:225], s[30:31], 0, v[130:131]
	s_add_i32 m0, s34, 0x2000
	s_nop 0
	global_load_lds_dwordx4 v[224:225], off
	v_lshl_add_u64 v[224:225], v[228:229], 0, s[10:11]
	s_mov_b32 m0, s65
	s_nop 0
	global_load_lds_dwordx4 v[224:225], off
	v_lshl_add_u64 v[224:225], v[230:231], 0, s[10:11]
	s_mov_b32 m0, s66
	s_nop 0
	global_load_lds_dwordx4 v[224:225], off
	s_nop 0
	s_nop 0
	s_nop 0
	s_waitcnt vmcnt(8)
	s_waitcnt lgkmcnt(0)
	s_barrier
	v_mfma_f32_16x16x32_bf16 v[110:113], v[154:157], v[192:195], v[110:113]
	v_mfma_f32_16x16x32_bf16 v[86:89], v[168:171], v[192:195], v[86:89]
	v_mfma_f32_16x16x32_bf16 v[106:109], v[154:157], v[200:203], v[106:109]
	v_mfma_f32_16x16x32_bf16 v[82:85], v[168:171], v[200:203], v[82:85]
	v_mfma_f32_16x16x32_bf16 v[118:121], v[154:157], v[208:211], v[118:121]
	v_mfma_f32_16x16x32_bf16 v[94:97], v[168:171], v[208:211], v[94:97]
	v_mfma_f32_16x16x32_bf16 v[126:129], v[154:157], v[216:219], v[126:129]
	v_mfma_f32_16x16x32_bf16 v[102:105], v[168:171], v[216:219], v[102:105]
	v_mfma_f32_16x16x32_bf16 v[110:113], v[164:167], v[196:199], v[110:113]
	v_mfma_f32_16x16x32_bf16 v[86:89], v[172:175], v[196:199], v[86:89]
	v_mfma_f32_16x16x32_bf16 v[106:109], v[164:167], v[204:207], v[106:109]
	v_mfma_f32_16x16x32_bf16 v[82:85], v[172:175], v[204:207], v[82:85]
	v_mfma_f32_16x16x32_bf16 v[118:121], v[164:167], v[212:215], v[118:121]
	v_mfma_f32_16x16x32_bf16 v[94:97], v[172:175], v[212:215], v[94:97]
	v_mfma_f32_16x16x32_bf16 v[126:129], v[164:167], v[220:223], v[126:129]
	v_mfma_f32_16x16x32_bf16 v[102:105], v[172:175], v[220:223], v[102:105]
	v_mfma_f32_16x16x32_bf16 v[70:73], v[176:179], v[192:195], v[70:73]
	v_mfma_f32_16x16x32_bf16 v[58:61], v[184:187], v[192:195], v[58:61]
	v_mfma_f32_16x16x32_bf16 v[74:77], v[176:179], v[200:203], v[74:77]
	v_mfma_f32_16x16x32_bf16 v[78:81], v[184:187], v[200:203], v[78:81]
	v_mfma_f32_16x16x32_bf16 v[114:117], v[176:179], v[208:211], v[114:117]
	v_mfma_f32_16x16x32_bf16 v[90:93], v[184:187], v[208:211], v[90:93]
	v_mfma_f32_16x16x32_bf16 v[122:125], v[176:179], v[216:219], v[122:125]
	v_mfma_f32_16x16x32_bf16 v[98:101], v[184:187], v[216:219], v[98:101]
	v_mfma_f32_16x16x32_bf16 v[70:73], v[180:183], v[196:199], v[70:73]
	v_mfma_f32_16x16x32_bf16 v[58:61], v[188:191], v[196:199], v[58:61]
	v_mfma_f32_16x16x32_bf16 v[74:77], v[180:183], v[204:207], v[74:77]
	v_mfma_f32_16x16x32_bf16 v[78:81], v[188:191], v[204:207], v[78:81]
	v_mfma_f32_16x16x32_bf16 v[114:117], v[180:183], v[212:215], v[114:117]
	v_mfma_f32_16x16x32_bf16 v[90:93], v[188:191], v[212:215], v[90:93]
	v_mfma_f32_16x16x32_bf16 v[122:125], v[180:183], v[220:223], v[122:125]
	v_mfma_f32_16x16x32_bf16 v[98:101], v[188:191], v[220:223], v[98:101]
	s_barrier
	s_add_u32 s28, s28, 0x100
	s_addc_u32 s29, s29, 0
	s_add_u32 s17, s17, 0x100
	s_addc_u32 s19, s19, 0
	s_cmp_ge_i32 s75, s62
	s_mov_b32 s30, s75
	s_cbranch_scc0 .LBB0_256

.LBB0_351:
	v_add_u32_e32 v81, s62, v78
	s_waitcnt lgkmcnt(0)
	ds_read_b128 v[82:85], v81
	ds_read_b128 v[86:89], v81 offset:1024
	ds_read_b128 v[90:93], v81 offset:2048
	ds_read_b128 v[94:97], v81 offset:3072
	s_add_i32 s72, s24, 2
	s_add_u32 s22, s20, 0x100
	s_addc_u32 s23, s21, 0
	s_cmp_eq_u32 s61, s24
	s_cselect_b32 s24, s16, s70
	s_cselect_b32 s27, s15, s23
	s_cselect_b32 s26, s14, s22
	s_cselect_b32 s25, s17, s71
	s_mov_b32 m0, s63
	v_lshl_add_u64 v[130:131], s[20:21], 0, v[74:75]
	ds_read_b128 v[98:101], v79
	ds_read_b128 v[102:105], v79 offset:1024
	ds_read_b128 v[106:109], v79 offset:2048
	ds_read_b128 v[110:113], v79 offset:3072
	ds_read_b128 v[114:117], v79 offset:4096
	ds_read_b128 v[118:121], v79 offset:5120
	ds_read_b128 v[122:125], v79 offset:6144
	ds_read_b128 v[126:129], v79 offset:7168
	global_load_lds_dwordx4 v[130:131], off
	v_lshl_add_u64 v[130:131], s[20:21], 0, v[76:77]
	s_mov_b32 m0, s64
	s_nop 0
	global_load_lds_dwordx4 v[130:131], off
	s_waitcnt vmcnt(8)
	s_waitcnt lgkmcnt(0)
	s_barrier
	v_mfma_f32_16x16x32_bf16 v[62:65], v[82:85], v[98:101], v[62:65]
	v_mfma_f32_16x16x32_bf16 v[58:61], v[90:93], v[98:101], v[58:61]
	v_mfma_f32_16x16x32_bf16 v[54:57], v[82:85], v[106:109], v[54:57]
	v_mfma_f32_16x16x32_bf16 v[50:53], v[90:93], v[106:109], v[50:53]
	v_mfma_f32_16x16x32_bf16 v[46:49], v[82:85], v[114:117], v[46:49]
	v_mfma_f32_16x16x32_bf16 v[42:45], v[90:93], v[114:117], v[42:45]
	v_mfma_f32_16x16x32_bf16 v[34:37], v[82:85], v[122:125], v[34:37]
	v_mfma_f32_16x16x32_bf16 v[26:29], v[90:93], v[122:125], v[26:29]
	v_mfma_f32_16x16x32_bf16 v[62:65], v[86:89], v[102:105], v[62:65]
	v_mfma_f32_16x16x32_bf16 v[58:61], v[94:97], v[102:105], v[58:61]
	v_mfma_f32_16x16x32_bf16 v[54:57], v[86:89], v[110:113], v[54:57]
	v_mfma_f32_16x16x32_bf16 v[50:53], v[94:97], v[110:113], v[50:53]
	v_mfma_f32_16x16x32_bf16 v[46:49], v[86:89], v[118:121], v[46:49]
	v_mfma_f32_16x16x32_bf16 v[42:45], v[94:97], v[118:121], v[42:45]
	v_mfma_f32_16x16x32_bf16 v[34:37], v[86:89], v[126:129], v[34:37]
	v_mfma_f32_16x16x32_bf16 v[26:29], v[94:97], v[126:129], v[26:29]
	s_barrier
	s_mov_b32 m0, s65
	v_lshl_add_u64 v[130:131], s[24:25], 0, v[70:71]
	s_add_u32 s20, s24, 0x10000
	ds_read_b128 v[98:101], v79 offset:16384
	ds_read_b128 v[102:105], v79 offset:17408
	ds_read_b128 v[106:109], v79 offset:18432
	ds_read_b128 v[110:113], v79 offset:19456
	ds_read_b128 v[114:117], v79 offset:20480
	ds_read_b128 v[118:121], v79 offset:21504
	ds_read_b128 v[122:125], v79 offset:22528
	ds_read_b128 v[126:129], v79 offset:23552
	global_load_lds_dwordx4 v[130:131], off
	v_lshl_add_u64 v[132:133], s[24:25], 0, v[66:67]
	s_mov_b32 m0, s66
	s_addc_u32 s21, s25, 0
	global_load_lds_dwordx4 v[132:133], off
	v_lshl_add_u64 v[134:135], s[20:21], 0, v[70:71]
	s_mov_b32 m0, s34
	v_lshl_add_u64 v[136:137], s[26:27], 0, v[68:69]
	global_load_lds_dwordx4 v[134:135], off
	v_lshl_add_u64 v[134:135], s[20:21], 0, v[66:67]
	s_mov_b32 m0, s35
	s_nop 0
	global_load_lds_dwordx4 v[134:135], off
	v_lshl_add_u64 v[134:135], s[26:27], 0, v[72:73]
	s_mov_b32 m0, s31
	s_nop 0
	global_load_lds_dwordx4 v[134:135], off
	s_mov_b32 m0, s52
	s_nop 0
	global_load_lds_dwordx4 v[136:137], off
	s_nop 0
	s_nop 0
	s_nop 0
	s_nop 0
	s_nop 0
	s_nop 0
	s_nop 0
	s_nop 0
	s_waitcnt vmcnt(8)
	s_waitcnt lgkmcnt(0)
	s_barrier
	v_mfma_f32_16x16x32_bf16 v[38:41], v[82:85], v[98:101], v[38:41]
	v_mfma_f32_16x16x32_bf16 v[30:33], v[90:93], v[98:101], v[30:33]
	v_mfma_f32_16x16x32_bf16 v[22:25], v[82:85], v[106:109], v[22:25]
	v_mfma_f32_16x16x32_bf16 v[18:21], v[90:93], v[106:109], v[18:21]
	v_mfma_f32_16x16x32_bf16 v[14:17], v[82:85], v[114:117], v[14:17]
	v_mfma_f32_16x16x32_bf16 v[10:13], v[90:93], v[114:117], v[10:13]
	v_mfma_f32_16x16x32_bf16 v[6:9], v[82:85], v[122:125], v[6:9]
	v_mfma_f32_16x16x32_bf16 v[2:5], v[90:93], v[122:125], v[2:5]
	v_mfma_f32_16x16x32_bf16 v[38:41], v[86:89], v[102:105], v[38:41]
	v_mfma_f32_16x16x32_bf16 v[30:33], v[94:97], v[102:105], v[30:33]
	v_mfma_f32_16x16x32_bf16 v[22:25], v[86:89], v[110:113], v[22:25]
	v_mfma_f32_16x16x32_bf16 v[18:21], v[94:97], v[110:113], v[18:21]
	v_mfma_f32_16x16x32_bf16 v[14:17], v[86:89], v[118:121], v[14:17]
	v_mfma_f32_16x16x32_bf16 v[10:13], v[94:97], v[118:121], v[10:13]
	v_mfma_f32_16x16x32_bf16 v[6:9], v[86:89], v[126:129], v[6:9]
	v_mfma_f32_16x16x32_bf16 v[2:5], v[94:97], v[126:129], v[2:5]
	s_barrier
	v_add_u32_e32 v81, s67, v78
	ds_read_b128 v[82:85], v81
	ds_read_b128 v[86:89], v81 offset:1024
	ds_read_b128 v[90:93], v81 offset:2048
	ds_read_b128 v[94:97], v81 offset:3072
	s_add_u32 s20, s26, 0x18000
	s_addc_u32 s21, s27, 0
	s_mov_b32 m0, s53
	v_lshl_add_u64 v[138:139], s[20:21], 0, v[72:73]
	ds_read_b128 v[98:101], v79 offset:32768
	ds_read_b128 v[102:105], v79 offset:33792
	ds_read_b128 v[106:109], v79 offset:34816
	ds_read_b128 v[110:113], v79 offset:35840
	ds_read_b128 v[114:117], v79 offset:36864
	ds_read_b128 v[118:121], v79 offset:37888
	ds_read_b128 v[122:125], v79 offset:38912
	ds_read_b128 v[126:129], v79 offset:39936
	global_load_lds_dwordx4 v[138:139], off
	v_lshl_add_u64 v[138:139], s[20:21], 0, v[68:69]
	s_mov_b32 m0, s54
	s_nop 0
	global_load_lds_dwordx4 v[138:139], off
	s_nop 0
	s_nop 0
	s_nop 0
	s_nop 0
	s_nop 0
	s_waitcnt vmcnt(8)
	s_waitcnt lgkmcnt(0)
	s_barrier
	v_mfma_f32_16x16x32_bf16 v[62:65], v[82:85], v[98:101], v[62:65]
	v_mfma_f32_16x16x32_bf16 v[58:61], v[90:93], v[98:101], v[58:61]
	v_mfma_f32_16x16x32_bf16 v[54:57], v[82:85], v[106:109], v[54:57]
	v_mfma_f32_16x16x32_bf16 v[50:53], v[90:93], v[106:109], v[50:53]
	v_mfma_f32_16x16x32_bf16 v[46:49], v[82:85], v[114:117], v[46:49]
	v_mfma_f32_16x16x32_bf16 v[42:45], v[90:93], v[114:117], v[42:45]
	v_mfma_f32_16x16x32_bf16 v[34:37], v[82:85], v[122:125], v[34:37]
	v_mfma_f32_16x16x32_bf16 v[26:29], v[90:93], v[122:125], v[26:29]
	v_mfma_f32_16x16x32_bf16 v[62:65], v[86:89], v[102:105], v[62:65]
	v_mfma_f32_16x16x32_bf16 v[58:61], v[94:97], v[102:105], v[58:61]
	v_mfma_f32_16x16x32_bf16 v[54:57], v[86:89], v[110:113], v[54:57]
	v_mfma_f32_16x16x32_bf16 v[50:53], v[94:97], v[110:113], v[50:53]
	v_mfma_f32_16x16x32_bf16 v[46:49], v[86:89], v[118:121], v[46:49]
	v_mfma_f32_16x16x32_bf16 v[42:45], v[94:97], v[118:121], v[42:45]
	v_mfma_f32_16x16x32_bf16 v[34:37], v[86:89], v[126:129], v[34:37]
	v_mfma_f32_16x16x32_bf16 v[26:29], v[94:97], v[126:129], v[26:29]
	s_barrier
	s_mov_b32 m0, s68
	v_lshl_add_u64 v[130:131], v[130:131], 0, s[6:7]
	s_add_u32 s20, s24, 0x10080
	ds_read_b128 v[98:101], v79 offset:49152
	ds_read_b128 v[102:105], v79 offset:50176
	ds_read_b128 v[106:109], v79 offset:51200
	ds_read_b128 v[110:113], v79 offset:52224
	ds_read_b128 v[114:117], v79 offset:53248
	ds_read_b128 v[118:121], v79 offset:54272
	ds_read_b128 v[122:125], v79 offset:55296
	ds_read_b128 v[126:129], v79 offset:56320
	global_load_lds_dwordx4 v[130:131], off
	v_lshl_add_u64 v[130:131], v[132:133], 0, s[6:7]
	s_mov_b32 m0, s69
	s_addc_u32 s21, s25, 0
	global_load_lds_dwordx4 v[130:131], off
	v_lshl_add_u64 v[130:131], s[20:21], 0, v[70:71]
	s_mov_b32 m0, s59
	s_nop 0
	global_load_lds_dwordx4 v[130:131], off
	v_lshl_add_u64 v[130:131], s[20:21], 0, v[66:67]
	s_mov_b32 m0, s60
	s_nop 0
	global_load_lds_dwordx4 v[130:131], off
	v_lshl_add_u64 v[130:131], v[134:135], 0, s[6:7]
	s_mov_b32 m0, s57
	s_nop 0
	global_load_lds_dwordx4 v[130:131], off
	v_lshl_add_u64 v[130:131], v[136:137], 0, s[6:7]
	s_mov_b32 m0, s58
	s_nop 0
	global_load_lds_dwordx4 v[130:131], off
	s_nop 0
	s_nop 0
	s_nop 0
	s_nop 0
	s_nop 0
	s_nop 0
	s_nop 0
	s_waitcnt vmcnt(8)
	s_waitcnt lgkmcnt(0)
	s_barrier
	v_mfma_f32_16x16x32_bf16 v[38:41], v[82:85], v[98:101], v[38:41]
	v_mfma_f32_16x16x32_bf16 v[30:33], v[90:93], v[98:101], v[30:33]
	v_mfma_f32_16x16x32_bf16 v[22:25], v[82:85], v[106:109], v[22:25]
	v_mfma_f32_16x16x32_bf16 v[18:21], v[90:93], v[106:109], v[18:21]
	v_mfma_f32_16x16x32_bf16 v[14:17], v[82:85], v[114:117], v[14:17]
	v_mfma_f32_16x16x32_bf16 v[10:13], v[90:93], v[114:117], v[10:13]
	v_mfma_f32_16x16x32_bf16 v[6:9], v[82:85], v[122:125], v[6:9]
	v_mfma_f32_16x16x32_bf16 v[2:5], v[90:93], v[122:125], v[2:5]
	v_mfma_f32_16x16x32_bf16 v[38:41], v[86:89], v[102:105], v[38:41]
	v_mfma_f32_16x16x32_bf16 v[30:33], v[94:97], v[102:105], v[30:33]
	v_mfma_f32_16x16x32_bf16 v[22:25], v[86:89], v[110:113], v[22:25]
	v_mfma_f32_16x16x32_bf16 v[18:21], v[94:97], v[110:113], v[18:21]
	v_mfma_f32_16x16x32_bf16 v[14:17], v[86:89], v[118:121], v[14:17]
	v_mfma_f32_16x16x32_bf16 v[10:13], v[94:97], v[118:121], v[10:13]
	v_mfma_f32_16x16x32_bf16 v[6:9], v[86:89], v[126:129], v[6:9]
	v_mfma_f32_16x16x32_bf16 v[2:5], v[94:97], v[126:129], v[2:5]
	s_barrier
	s_add_u32 s70, s70, 0x100
	s_addc_u32 s71, s71, 0
	s_cmp_ge_i32 s72, s56
	s_mov_b64 s[20:21], s[22:23]
	s_mov_b32 s24, s72
	s_cbranch_scc0 .LBB0_351

.LBB0_468:
	v_add_u32_e32 v144, s62, v1
	ds_read_b128 v[150:153], v144
	ds_read_b128 v[154:157], v144 offset:1024
	ds_read_b128 v[158:161], v144 offset:2048
	ds_read_b128 v[162:165], v144 offset:3072
	v_add_u32_e32 v144, s63, v1
	ds_read_b128 v[166:169], v144
	ds_read_b128 v[170:173], v144 offset:1024
	ds_read_b128 v[174:177], v144 offset:2048
	ds_read_b128 v[178:181], v144 offset:3072
	s_add_i32 s77, s26, 2
	s_add_u32 s24, s22, 0x100
	s_addc_u32 s25, s23, 0
	s_cmp_eq_u32 s61, s26
	s_cselect_b32 s26, s16, s75
	s_cselect_b32 s29, s15, s25
	s_cselect_b32 s28, s14, s24
	s_cselect_b32 s27, s17, s76
	s_mov_b32 m0, s64
	v_lshl_add_u64 v[144:145], s[22:23], 0, v[140:141]
	ds_read_b128 v[182:185], v149
	ds_read_b128 v[186:189], v149 offset:1024
	ds_read_b128 v[190:193], v149 offset:2048
	ds_read_b128 v[194:197], v149 offset:3072
	ds_read_b128 v[198:201], v149 offset:4096
	ds_read_b128 v[202:205], v149 offset:5120
	ds_read_b128 v[206:209], v149 offset:6144
	ds_read_b128 v[210:213], v149 offset:7168
	global_load_lds_dwordx4 v[144:145], off
	v_lshl_add_u64 v[144:145], s[22:23], 0, v[142:143]
	s_mov_b32 m0, s65
	s_nop 0
	global_load_lds_dwordx4 v[144:145], off
	s_nop 0
	s_nop 0
	s_nop 0
	s_nop 0
	s_nop 0
	s_nop 0
	s_nop 0
	s_nop 0
	s_waitcnt vmcnt(8)
	s_waitcnt lgkmcnt(0)
	s_barrier
	v_mfma_f32_16x16x32_bf16 v[126:129], v[150:153], v[182:185], v[126:129]
	v_mfma_f32_16x16x32_bf16 v[122:125], v[158:161], v[182:185], v[122:125]
	v_mfma_f32_16x16x32_bf16 v[110:113], v[150:153], v[190:193], v[110:113]
	v_mfma_f32_16x16x32_bf16 v[106:109], v[158:161], v[190:193], v[106:109]
	v_mfma_f32_16x16x32_bf16 v[94:97], v[150:153], v[198:201], v[94:97]
	v_mfma_f32_16x16x32_bf16 v[90:93], v[158:161], v[198:201], v[90:93]
	v_mfma_f32_16x16x32_bf16 v[78:81], v[150:153], v[206:209], v[78:81]
	v_mfma_f32_16x16x32_bf16 v[74:77], v[158:161], v[206:209], v[74:77]
	v_mfma_f32_16x16x32_bf16 v[126:129], v[154:157], v[186:189], v[126:129]
	v_mfma_f32_16x16x32_bf16 v[122:125], v[162:165], v[186:189], v[122:125]
	v_mfma_f32_16x16x32_bf16 v[110:113], v[154:157], v[194:197], v[110:113]
	v_mfma_f32_16x16x32_bf16 v[106:109], v[162:165], v[194:197], v[106:109]
	v_mfma_f32_16x16x32_bf16 v[94:97], v[154:157], v[202:205], v[94:97]
	v_mfma_f32_16x16x32_bf16 v[90:93], v[162:165], v[202:205], v[90:93]
	v_mfma_f32_16x16x32_bf16 v[78:81], v[154:157], v[210:213], v[78:81]
	v_mfma_f32_16x16x32_bf16 v[74:77], v[162:165], v[210:213], v[74:77]
	v_mfma_f32_16x16x32_bf16 v[118:121], v[166:169], v[182:185], v[118:121]
	v_mfma_f32_16x16x32_bf16 v[114:117], v[174:177], v[182:185], v[114:117]
	v_mfma_f32_16x16x32_bf16 v[102:105], v[166:169], v[190:193], v[102:105]
	v_mfma_f32_16x16x32_bf16 v[98:101], v[174:177], v[190:193], v[98:101]
	v_mfma_f32_16x16x32_bf16 v[86:89], v[166:169], v[198:201], v[86:89]
	v_mfma_f32_16x16x32_bf16 v[82:85], v[174:177], v[198:201], v[82:85]
	v_mfma_f32_16x16x32_bf16 v[70:73], v[166:169], v[206:209], v[70:73]
	v_mfma_f32_16x16x32_bf16 v[66:69], v[174:177], v[206:209], v[66:69]
	v_mfma_f32_16x16x32_bf16 v[118:121], v[170:173], v[186:189], v[118:121]
	v_mfma_f32_16x16x32_bf16 v[114:117], v[178:181], v[186:189], v[114:117]
	v_mfma_f32_16x16x32_bf16 v[102:105], v[170:173], v[194:197], v[102:105]
	v_mfma_f32_16x16x32_bf16 v[98:101], v[178:181], v[194:197], v[98:101]
	v_mfma_f32_16x16x32_bf16 v[86:89], v[170:173], v[202:205], v[86:89]
	v_mfma_f32_16x16x32_bf16 v[82:85], v[178:181], v[202:205], v[82:85]
	v_mfma_f32_16x16x32_bf16 v[70:73], v[170:173], v[210:213], v[70:73]
	v_mfma_f32_16x16x32_bf16 v[66:69], v[178:181], v[210:213], v[66:69]
	s_barrier
	s_mov_b32 m0, s66
	v_lshl_add_u64 v[144:145], s[26:27], 0, v[134:135]
	s_add_u32 s22, s26, 0x18000
	ds_read_b128 v[182:185], v149 offset:16384
	ds_read_b128 v[186:189], v149 offset:17408
	ds_read_b128 v[190:193], v149 offset:18432
	ds_read_b128 v[194:197], v149 offset:19456
	ds_read_b128 v[198:201], v149 offset:20480
	ds_read_b128 v[202:205], v149 offset:21504
	ds_read_b128 v[206:209], v149 offset:22528
	ds_read_b128 v[210:213], v149 offset:23552
	global_load_lds_dwordx4 v[144:145], off
	v_lshl_add_u64 v[214:215], s[26:27], 0, v[130:131]
	s_mov_b32 m0, s67
	s_addc_u32 s23, s27, 0
	global_load_lds_dwordx4 v[214:215], off
	v_lshl_add_u64 v[216:217], s[22:23], 0, v[134:135]
	s_mov_b32 m0, s68
	v_lshl_add_u64 v[218:219], s[28:29], 0, v[132:133]
	global_load_lds_dwordx4 v[216:217], off
	v_lshl_add_u64 v[216:217], s[22:23], 0, v[130:131]
	s_mov_b32 m0, s69
	s_nop 0
	global_load_lds_dwordx4 v[216:217], off
	v_lshl_add_u64 v[216:217], s[28:29], 0, v[136:137]
	s_mov_b32 m0, s34
	s_nop 0
	global_load_lds_dwordx4 v[216:217], off
	s_mov_b32 m0, s35
	s_nop 0
	global_load_lds_dwordx4 v[218:219], off
	s_nop 0
	s_nop 0
	s_nop 0
	s_nop 0
	s_nop 0
	s_nop 0
	s_nop 0
	s_nop 0
	s_waitcnt vmcnt(8)
	s_waitcnt lgkmcnt(0)
	s_barrier
	v_mfma_f32_16x16x32_bf16 v[62:65], v[150:153], v[182:185], v[62:65]
	v_mfma_f32_16x16x32_bf16 v[58:61], v[158:161], v[182:185], v[58:61]
	v_mfma_f32_16x16x32_bf16 v[46:49], v[150:153], v[190:193], v[46:49]
	v_mfma_f32_16x16x32_bf16 v[42:45], v[158:161], v[190:193], v[42:45]
	v_mfma_f32_16x16x32_bf16 v[30:33], v[150:153], v[198:201], v[30:33]
	v_mfma_f32_16x16x32_bf16 v[26:29], v[158:161], v[198:201], v[26:29]
	v_mfma_f32_16x16x32_bf16 v[14:17], v[150:153], v[206:209], v[14:17]
	v_mfma_f32_16x16x32_bf16 v[10:13], v[158:161], v[206:209], v[10:13]
	v_mfma_f32_16x16x32_bf16 v[62:65], v[154:157], v[186:189], v[62:65]
	v_mfma_f32_16x16x32_bf16 v[58:61], v[162:165], v[186:189], v[58:61]
	v_mfma_f32_16x16x32_bf16 v[46:49], v[154:157], v[194:197], v[46:49]
	v_mfma_f32_16x16x32_bf16 v[42:45], v[162:165], v[194:197], v[42:45]
	v_mfma_f32_16x16x32_bf16 v[30:33], v[154:157], v[202:205], v[30:33]
	v_mfma_f32_16x16x32_bf16 v[26:29], v[162:165], v[202:205], v[26:29]
	v_mfma_f32_16x16x32_bf16 v[14:17], v[154:157], v[210:213], v[14:17]
	v_mfma_f32_16x16x32_bf16 v[10:13], v[162:165], v[210:213], v[10:13]
	v_mfma_f32_16x16x32_bf16 v[54:57], v[166:169], v[182:185], v[54:57]
	v_mfma_f32_16x16x32_bf16 v[50:53], v[174:177], v[182:185], v[50:53]
	v_mfma_f32_16x16x32_bf16 v[38:41], v[166:169], v[190:193], v[38:41]
	v_mfma_f32_16x16x32_bf16 v[34:37], v[174:177], v[190:193], v[34:37]
	v_mfma_f32_16x16x32_bf16 v[22:25], v[166:169], v[198:201], v[22:25]
	v_mfma_f32_16x16x32_bf16 v[18:21], v[174:177], v[198:201], v[18:21]
	v_mfma_f32_16x16x32_bf16 v[6:9], v[166:169], v[206:209], v[6:9]
	v_mfma_f32_16x16x32_bf16 v[2:5], v[174:177], v[206:209], v[2:5]
	v_mfma_f32_16x16x32_bf16 v[54:57], v[170:173], v[186:189], v[54:57]
	v_mfma_f32_16x16x32_bf16 v[50:53], v[178:181], v[186:189], v[50:53]
	v_mfma_f32_16x16x32_bf16 v[38:41], v[170:173], v[194:197], v[38:41]
	v_mfma_f32_16x16x32_bf16 v[34:37], v[178:181], v[194:197], v[34:37]
	v_mfma_f32_16x16x32_bf16 v[22:25], v[170:173], v[202:205], v[22:25]
	v_mfma_f32_16x16x32_bf16 v[18:21], v[178:181], v[202:205], v[18:21]
	v_mfma_f32_16x16x32_bf16 v[6:9], v[170:173], v[210:213], v[6:9]
	v_mfma_f32_16x16x32_bf16 v[2:5], v[178:181], v[210:213], v[2:5]
	s_barrier
	v_add_u32_e32 v162, s70, v1
	v_add_u32_e32 v178, s71, v1
	ds_read_b128 v[150:153], v162
	ds_read_b128 v[154:157], v162 offset:1024
	ds_read_b128 v[158:161], v162 offset:2048
	ds_read_b128 v[162:165], v162 offset:3072
	ds_read_b128 v[166:169], v178
	ds_read_b128 v[170:173], v178 offset:1024
	ds_read_b128 v[174:177], v178 offset:2048
	ds_read_b128 v[178:181], v178 offset:3072
	s_add_u32 s22, s28, 0x18000
	s_addc_u32 s23, s29, 0
	s_mov_b32 m0, s52
	v_lshl_add_u64 v[220:221], s[22:23], 0, v[136:137]
	ds_read_b128 v[182:185], v149 offset:32768
	ds_read_b128 v[186:189], v149 offset:33792
	ds_read_b128 v[190:193], v149 offset:34816
	ds_read_b128 v[194:197], v149 offset:35840
	ds_read_b128 v[198:201], v149 offset:36864
	ds_read_b128 v[202:205], v149 offset:37888
	ds_read_b128 v[206:209], v149 offset:38912
	ds_read_b128 v[210:213], v149 offset:39936
	global_load_lds_dwordx4 v[220:221], off
	v_lshl_add_u64 v[220:221], s[22:23], 0, v[132:133]
	s_mov_b32 m0, s53
	s_nop 0
	global_load_lds_dwordx4 v[220:221], off
	s_nop 0
	s_nop 0
	s_nop 0
	s_nop 0
	s_nop 0
	s_nop 0
	s_nop 0
	s_nop 0
	s_nop 0
	s_nop 0
	s_nop 0
	s_nop 0
	s_waitcnt vmcnt(8)
	s_waitcnt lgkmcnt(0)
	s_barrier
	v_mfma_f32_16x16x32_bf16 v[126:129], v[150:153], v[182:185], v[126:129]
	v_mfma_f32_16x16x32_bf16 v[122:125], v[158:161], v[182:185], v[122:125]
	v_mfma_f32_16x16x32_bf16 v[110:113], v[150:153], v[190:193], v[110:113]
	v_mfma_f32_16x16x32_bf16 v[106:109], v[158:161], v[190:193], v[106:109]
	v_mfma_f32_16x16x32_bf16 v[94:97], v[150:153], v[198:201], v[94:97]
	v_mfma_f32_16x16x32_bf16 v[90:93], v[158:161], v[198:201], v[90:93]
	v_mfma_f32_16x16x32_bf16 v[78:81], v[150:153], v[206:209], v[78:81]
	v_mfma_f32_16x16x32_bf16 v[74:77], v[158:161], v[206:209], v[74:77]
	v_mfma_f32_16x16x32_bf16 v[126:129], v[154:157], v[186:189], v[126:129]
	v_mfma_f32_16x16x32_bf16 v[122:125], v[162:165], v[186:189], v[122:125]
	v_mfma_f32_16x16x32_bf16 v[110:113], v[154:157], v[194:197], v[110:113]
	v_mfma_f32_16x16x32_bf16 v[106:109], v[162:165], v[194:197], v[106:109]
	v_mfma_f32_16x16x32_bf16 v[94:97], v[154:157], v[202:205], v[94:97]
	v_mfma_f32_16x16x32_bf16 v[90:93], v[162:165], v[202:205], v[90:93]
	v_mfma_f32_16x16x32_bf16 v[78:81], v[154:157], v[210:213], v[78:81]
	v_mfma_f32_16x16x32_bf16 v[74:77], v[162:165], v[210:213], v[74:77]
	v_mfma_f32_16x16x32_bf16 v[118:121], v[166:169], v[182:185], v[118:121]
	v_mfma_f32_16x16x32_bf16 v[114:117], v[174:177], v[182:185], v[114:117]
	v_mfma_f32_16x16x32_bf16 v[102:105], v[166:169], v[190:193], v[102:105]
	v_mfma_f32_16x16x32_bf16 v[98:101], v[174:177], v[190:193], v[98:101]
	v_mfma_f32_16x16x32_bf16 v[86:89], v[166:169], v[198:201], v[86:89]
	v_mfma_f32_16x16x32_bf16 v[82:85], v[174:177], v[198:201], v[82:85]
	v_mfma_f32_16x16x32_bf16 v[70:73], v[166:169], v[206:209], v[70:73]
	v_mfma_f32_16x16x32_bf16 v[66:69], v[174:177], v[206:209], v[66:69]
	v_mfma_f32_16x16x32_bf16 v[118:121], v[170:173], v[186:189], v[118:121]
	v_mfma_f32_16x16x32_bf16 v[114:117], v[178:181], v[186:189], v[114:117]
	v_mfma_f32_16x16x32_bf16 v[102:105], v[170:173], v[194:197], v[102:105]
	v_mfma_f32_16x16x32_bf16 v[98:101], v[178:181], v[194:197], v[98:101]
	v_mfma_f32_16x16x32_bf16 v[86:89], v[170:173], v[202:205], v[86:89]
	v_mfma_f32_16x16x32_bf16 v[82:85], v[178:181], v[202:205], v[82:85]
	v_mfma_f32_16x16x32_bf16 v[70:73], v[170:173], v[210:213], v[70:73]
	v_mfma_f32_16x16x32_bf16 v[66:69], v[178:181], v[210:213], v[66:69]
	s_barrier
	s_mov_b32 m0, s72
	v_lshl_add_u64 v[144:145], v[144:145], 0, s[4:5]
	ds_read_b128 v[182:185], v149 offset:49152
	ds_read_b128 v[186:189], v149 offset:50176
	ds_read_b128 v[190:193], v149 offset:51200
	ds_read_b128 v[194:197], v149 offset:52224
	ds_read_b128 v[198:201], v149 offset:53248
	ds_read_b128 v[202:205], v149 offset:54272
	ds_read_b128 v[206:209], v149 offset:55296
	ds_read_b128 v[210:213], v149 offset:56320
	global_load_lds_dwordx4 v[144:145], off
	s_add_i32 m0, s72, 0x2000
	s_add_u32 s22, s26, 0x18080
	v_lshl_add_u64 v[144:145], v[214:215], 0, s[4:5]
	s_addc_u32 s23, s27, 0
	s_add_i32 s26, s71, s30
	global_load_lds_dwordx4 v[144:145], off
	v_lshl_add_u64 v[144:145], s[22:23], 0, v[134:135]
	s_mov_b32 m0, s26
	s_nop 0
	global_load_lds_dwordx4 v[144:145], off
	v_lshl_add_u64 v[144:145], s[22:23], 0, v[130:131]
	s_add_i32 m0, s26, 0x2000
	s_nop 0
	global_load_lds_dwordx4 v[144:145], off
	v_lshl_add_u64 v[144:145], v[216:217], 0, s[4:5]
	s_mov_b32 m0, s59
	s_nop 0
	global_load_lds_dwordx4 v[144:145], off
	v_lshl_add_u64 v[144:145], v[218:219], 0, s[4:5]
	s_mov_b32 m0, s60
	s_nop 0
	global_load_lds_dwordx4 v[144:145], off
	s_nop 0
	s_nop 0
	s_nop 0
	s_nop 0
	s_waitcnt vmcnt(8)
	s_waitcnt lgkmcnt(0)
	s_barrier
	v_mfma_f32_16x16x32_bf16 v[62:65], v[150:153], v[182:185], v[62:65]
	v_mfma_f32_16x16x32_bf16 v[58:61], v[158:161], v[182:185], v[58:61]
	v_mfma_f32_16x16x32_bf16 v[46:49], v[150:153], v[190:193], v[46:49]
	v_mfma_f32_16x16x32_bf16 v[42:45], v[158:161], v[190:193], v[42:45]
	v_mfma_f32_16x16x32_bf16 v[30:33], v[150:153], v[198:201], v[30:33]
	v_mfma_f32_16x16x32_bf16 v[26:29], v[158:161], v[198:201], v[26:29]
	v_mfma_f32_16x16x32_bf16 v[14:17], v[150:153], v[206:209], v[14:17]
	v_mfma_f32_16x16x32_bf16 v[10:13], v[158:161], v[206:209], v[10:13]
	v_mfma_f32_16x16x32_bf16 v[62:65], v[154:157], v[186:189], v[62:65]
	v_mfma_f32_16x16x32_bf16 v[58:61], v[162:165], v[186:189], v[58:61]
	v_mfma_f32_16x16x32_bf16 v[46:49], v[154:157], v[194:197], v[46:49]
	v_mfma_f32_16x16x32_bf16 v[42:45], v[162:165], v[194:197], v[42:45]
	v_mfma_f32_16x16x32_bf16 v[30:33], v[154:157], v[202:205], v[30:33]
	v_mfma_f32_16x16x32_bf16 v[26:29], v[162:165], v[202:205], v[26:29]
	v_mfma_f32_16x16x32_bf16 v[14:17], v[154:157], v[210:213], v[14:17]
	v_mfma_f32_16x16x32_bf16 v[10:13], v[162:165], v[210:213], v[10:13]
	v_mfma_f32_16x16x32_bf16 v[54:57], v[166:169], v[182:185], v[54:57]
	v_mfma_f32_16x16x32_bf16 v[50:53], v[174:177], v[182:185], v[50:53]
	v_mfma_f32_16x16x32_bf16 v[38:41], v[166:169], v[190:193], v[38:41]
	v_mfma_f32_16x16x32_bf16 v[34:37], v[174:177], v[190:193], v[34:37]
	v_mfma_f32_16x16x32_bf16 v[22:25], v[166:169], v[198:201], v[22:25]
	v_mfma_f32_16x16x32_bf16 v[18:21], v[174:177], v[198:201], v[18:21]
	v_mfma_f32_16x16x32_bf16 v[6:9], v[166:169], v[206:209], v[6:9]
	v_mfma_f32_16x16x32_bf16 v[2:5], v[174:177], v[206:209], v[2:5]
	v_mfma_f32_16x16x32_bf16 v[54:57], v[170:173], v[186:189], v[54:57]
	v_mfma_f32_16x16x32_bf16 v[50:53], v[178:181], v[186:189], v[50:53]
	v_mfma_f32_16x16x32_bf16 v[38:41], v[170:173], v[194:197], v[38:41]
	v_mfma_f32_16x16x32_bf16 v[34:37], v[178:181], v[194:197], v[34:37]
	v_mfma_f32_16x16x32_bf16 v[22:25], v[170:173], v[202:205], v[22:25]
	v_mfma_f32_16x16x32_bf16 v[18:21], v[178:181], v[202:205], v[18:21]
	v_mfma_f32_16x16x32_bf16 v[6:9], v[170:173], v[210:213], v[6:9]
	v_mfma_f32_16x16x32_bf16 v[2:5], v[178:181], v[210:213], v[2:5]
	s_barrier
	s_add_u32 s75, s75, 0x100
	s_addc_u32 s76, s76, 0
	s_cmp_ge_i32 s77, s57
	s_mov_b64 s[22:23], s[24:25]
	s_mov_b32 s26, s77
	s_cbranch_scc0 .LBB0_468

.LBB0_599:
	v_add_u32_e32 v142, s74, v199
	v_add_u32_e32 v162, s75, v199
	ds_read_b128 v[130:133], v142
	ds_read_b128 v[134:137], v142 offset:1024
	ds_read_b128 v[138:141], v142 offset:2048
	ds_read_b128 v[142:145], v142 offset:3072
	ds_read_b128 v[146:149], v162
	ds_read_b128 v[150:153], v162 offset:1024
	ds_read_b128 v[174:177], v162 offset:2048
	ds_read_b128 v[178:181], v162 offset:3072
	s_add_i32 s31, s52, 2
	s_add_u32 s50, s34, 0x3ff000
	s_addc_u32 s51, s35, 0
	s_cmp_eq_u32 s71, s52
	s_cselect_b32 s56, s26, s50
	s_cselect_b32 s57, s27, s51
	s_cselect_b32 s54, s28, s23
	s_cselect_b32 s55, s29, s25
	s_add_u32 s52, s56, 0x400000
	s_addc_u32 s53, s57, 0
	v_lshl_add_u64 v[218:219], s[34:35], 0, v[164:165]
	s_add_i32 m0, s59, 0xc000
	ds_read_b128 v[182:185], v200
	ds_read_b128 v[186:189], v200 offset:1024
	ds_read_b128 v[190:193], v200 offset:2048
	ds_read_b128 v[194:197], v200 offset:3072
	ds_read_b128 v[202:205], v200 offset:4096
	ds_read_b128 v[206:209], v200 offset:5120
	ds_read_b128 v[210:213], v200 offset:6144
	ds_read_b128 v[214:217], v200 offset:7168
	global_load_lds_dwordx4 v[218:219], off
	v_lshl_add_u64 v[218:219], s[34:35], 0, v[166:167]
	s_add_i32 m0, s59, 0xe000
	s_nop 0
	global_load_lds_dwordx4 v[218:219], off
	s_nop 0
	s_nop 0
	s_nop 0
	s_nop 0
	s_nop 0
	s_waitcnt vmcnt(8)
	s_waitcnt lgkmcnt(0)
	s_barrier
	v_mfma_f32_16x16x32_bf16 v[118:121], v[130:133], v[182:185], v[118:121]
	v_mfma_f32_16x16x32_bf16 v[122:125], v[138:141], v[182:185], v[122:125]
	v_mfma_f32_16x16x32_bf16 v[110:113], v[130:133], v[190:193], v[110:113]
	v_mfma_f32_16x16x32_bf16 v[106:109], v[138:141], v[190:193], v[106:109]
	v_mfma_f32_16x16x32_bf16 v[94:97], v[130:133], v[202:205], v[94:97]
	v_mfma_f32_16x16x32_bf16 v[90:93], v[138:141], v[202:205], v[90:93]
	v_mfma_f32_16x16x32_bf16 v[78:81], v[130:133], v[210:213], v[78:81]
	v_mfma_f32_16x16x32_bf16 v[74:77], v[138:141], v[210:213], v[74:77]
	v_mfma_f32_16x16x32_bf16 v[118:121], v[134:137], v[186:189], v[118:121]
	v_mfma_f32_16x16x32_bf16 v[122:125], v[142:145], v[186:189], v[122:125]
	v_mfma_f32_16x16x32_bf16 v[110:113], v[134:137], v[194:197], v[110:113]
	v_mfma_f32_16x16x32_bf16 v[106:109], v[142:145], v[194:197], v[106:109]
	v_mfma_f32_16x16x32_bf16 v[94:97], v[134:137], v[206:209], v[94:97]
	v_mfma_f32_16x16x32_bf16 v[90:93], v[142:145], v[206:209], v[90:93]
	v_mfma_f32_16x16x32_bf16 v[78:81], v[134:137], v[214:217], v[78:81]
	v_mfma_f32_16x16x32_bf16 v[74:77], v[142:145], v[214:217], v[74:77]
	v_mfma_f32_16x16x32_bf16 v[126:129], v[146:149], v[182:185], v[126:129]
	v_mfma_f32_16x16x32_bf16 v[114:117], v[174:177], v[182:185], v[114:117]
	v_mfma_f32_16x16x32_bf16 v[102:105], v[146:149], v[190:193], v[102:105]
	v_mfma_f32_16x16x32_bf16 v[98:101], v[174:177], v[190:193], v[98:101]
	v_mfma_f32_16x16x32_bf16 v[86:89], v[146:149], v[202:205], v[86:89]
	v_mfma_f32_16x16x32_bf16 v[82:85], v[174:177], v[202:205], v[82:85]
	v_mfma_f32_16x16x32_bf16 v[70:73], v[146:149], v[210:213], v[70:73]
	v_mfma_f32_16x16x32_bf16 v[66:69], v[174:177], v[210:213], v[66:69]
	v_mfma_f32_16x16x32_bf16 v[126:129], v[150:153], v[186:189], v[126:129]
	v_mfma_f32_16x16x32_bf16 v[114:117], v[178:181], v[186:189], v[114:117]
	v_mfma_f32_16x16x32_bf16 v[102:105], v[150:153], v[194:197], v[102:105]
	v_mfma_f32_16x16x32_bf16 v[98:101], v[178:181], v[194:197], v[98:101]
	v_mfma_f32_16x16x32_bf16 v[86:89], v[150:153], v[206:209], v[86:89]
	v_mfma_f32_16x16x32_bf16 v[82:85], v[178:181], v[206:209], v[82:85]
	v_mfma_f32_16x16x32_bf16 v[70:73], v[150:153], v[214:217], v[70:73]
	v_mfma_f32_16x16x32_bf16 v[66:69], v[178:181], v[214:217], v[66:69]
	s_barrier
	s_add_i32 s50, s74, s41
	v_lshl_add_u64 v[218:219], s[54:55], 0, v[156:157]
	s_mov_b32 m0, s50
	ds_read_b128 v[182:185], v200 offset:16384
	ds_read_b128 v[186:189], v200 offset:17408
	ds_read_b128 v[190:193], v200 offset:18432
	ds_read_b128 v[194:197], v200 offset:19456
	ds_read_b128 v[202:205], v200 offset:20480
	ds_read_b128 v[206:209], v200 offset:21504
	ds_read_b128 v[210:213], v200 offset:22528
	ds_read_b128 v[214:217], v200 offset:23552
	global_load_lds_dwordx4 v[218:219], off
	s_add_i32 m0, s50, 0x2000
	s_add_u32 s50, s54, 0x20000
	v_lshl_add_u64 v[220:221], s[54:55], 0, v[160:161]
	s_addc_u32 s51, s55, 0
	s_add_i32 s78, s75, s41
	global_load_lds_dwordx4 v[220:221], off
	v_lshl_add_u64 v[222:223], s[50:51], 0, v[156:157]
	s_mov_b32 m0, s78
	s_nop 0
	global_load_lds_dwordx4 v[222:223], off
	v_lshl_add_u64 v[222:223], s[50:51], 0, v[160:161]
	s_add_i32 m0, s78, 0x2000
	s_nop 0
	global_load_lds_dwordx4 v[222:223], off
	v_lshl_add_u64 v[222:223], s[56:57], 0, v[154:155]
	s_mov_b32 m0, s59
	s_nop 0
	global_load_lds_dwordx4 v[222:223], off
	v_lshl_add_u64 v[222:223], s[56:57], 0, v[158:159]
	s_mov_b32 m0, s60
	s_nop 0
	global_load_lds_dwordx4 v[222:223], off
	s_nop 0
	s_nop 0
	s_nop 0
	s_waitcnt vmcnt(8)
	s_waitcnt lgkmcnt(0)
	s_barrier
	v_mfma_f32_16x16x32_bf16 v[62:65], v[130:133], v[182:185], v[62:65]
	v_mfma_f32_16x16x32_bf16 v[58:61], v[138:141], v[182:185], v[58:61]
	v_mfma_f32_16x16x32_bf16 v[46:49], v[130:133], v[190:193], v[46:49]
	v_mfma_f32_16x16x32_bf16 v[42:45], v[138:141], v[190:193], v[42:45]
	v_mfma_f32_16x16x32_bf16 v[30:33], v[130:133], v[202:205], v[30:33]
	v_mfma_f32_16x16x32_bf16 v[26:29], v[138:141], v[202:205], v[26:29]
	v_mfma_f32_16x16x32_bf16 v[14:17], v[130:133], v[210:213], v[14:17]
	v_mfma_f32_16x16x32_bf16 v[10:13], v[138:141], v[210:213], v[10:13]
	v_mfma_f32_16x16x32_bf16 v[62:65], v[134:137], v[186:189], v[62:65]
	v_mfma_f32_16x16x32_bf16 v[58:61], v[142:145], v[186:189], v[58:61]
	v_mfma_f32_16x16x32_bf16 v[46:49], v[134:137], v[194:197], v[46:49]
	v_mfma_f32_16x16x32_bf16 v[42:45], v[142:145], v[194:197], v[42:45]
	v_mfma_f32_16x16x32_bf16 v[30:33], v[134:137], v[206:209], v[30:33]
	v_mfma_f32_16x16x32_bf16 v[26:29], v[142:145], v[206:209], v[26:29]
	v_mfma_f32_16x16x32_bf16 v[14:17], v[134:137], v[214:217], v[14:17]
	v_mfma_f32_16x16x32_bf16 v[10:13], v[142:145], v[214:217], v[10:13]
	v_mfma_f32_16x16x32_bf16 v[54:57], v[146:149], v[182:185], v[54:57]
	v_mfma_f32_16x16x32_bf16 v[50:53], v[174:177], v[182:185], v[50:53]
	v_mfma_f32_16x16x32_bf16 v[38:41], v[146:149], v[190:193], v[38:41]
	v_mfma_f32_16x16x32_bf16 v[34:37], v[174:177], v[190:193], v[34:37]
	v_mfma_f32_16x16x32_bf16 v[22:25], v[146:149], v[202:205], v[22:25]
	v_mfma_f32_16x16x32_bf16 v[18:21], v[174:177], v[202:205], v[18:21]
	v_mfma_f32_16x16x32_bf16 v[6:9], v[146:149], v[210:213], v[6:9]
	v_mfma_f32_16x16x32_bf16 v[2:5], v[174:177], v[210:213], v[2:5]
	v_mfma_f32_16x16x32_bf16 v[54:57], v[150:153], v[186:189], v[54:57]
	v_mfma_f32_16x16x32_bf16 v[50:53], v[178:181], v[186:189], v[50:53]
	v_mfma_f32_16x16x32_bf16 v[38:41], v[150:153], v[194:197], v[38:41]
	v_mfma_f32_16x16x32_bf16 v[34:37], v[178:181], v[194:197], v[34:37]
	v_mfma_f32_16x16x32_bf16 v[22:25], v[150:153], v[206:209], v[22:25]
	v_mfma_f32_16x16x32_bf16 v[18:21], v[178:181], v[206:209], v[18:21]
	v_mfma_f32_16x16x32_bf16 v[6:9], v[150:153], v[214:217], v[6:9]
	v_mfma_f32_16x16x32_bf16 v[2:5], v[178:181], v[214:217], v[2:5]
	s_barrier
	s_add_i32 s78, 0, 0x18000
	s_add_i32 s79, 0, 0x1c000
	v_add_u32_e32 v142, s78, v199
	v_add_u32_e32 v162, s79, v199
	ds_read_b128 v[130:133], v142
	ds_read_b128 v[134:137], v142 offset:1024
	ds_read_b128 v[138:141], v142 offset:2048
	ds_read_b128 v[142:145], v142 offset:3072
	ds_read_b128 v[146:149], v162
	ds_read_b128 v[150:153], v162 offset:1024
	ds_read_b128 v[174:177], v162 offset:2048
	ds_read_b128 v[178:181], v162 offset:3072
	s_add_u32 s50, s56, 0x1000
	s_addc_u32 s51, s57, 0
	s_mov_b32 m0, s61
	v_lshl_add_u64 v[222:223], s[50:51], 0, v[154:155]
	ds_read_b128 v[182:185], v200 offset:32768
	ds_read_b128 v[186:189], v200 offset:33792
	ds_read_b128 v[190:193], v200 offset:34816
	ds_read_b128 v[194:197], v200 offset:35840
	ds_read_b128 v[202:205], v200 offset:36864
	ds_read_b128 v[206:209], v200 offset:37888
	ds_read_b128 v[210:213], v200 offset:38912
	ds_read_b128 v[214:217], v200 offset:39936
	global_load_lds_dwordx4 v[222:223], off
	v_lshl_add_u64 v[222:223], s[50:51], 0, v[158:159]
	s_mov_b32 m0, s62
	s_nop 0
	global_load_lds_dwordx4 v[222:223], off
	s_nop 0
	s_nop 0
	s_nop 0
	s_nop 0
	s_nop 0
	s_nop 0
	s_nop 0
	s_nop 0
	s_waitcnt vmcnt(8)
	s_waitcnt lgkmcnt(0)
	s_barrier
	v_mfma_f32_16x16x32_bf16 v[118:121], v[130:133], v[182:185], v[118:121]
	v_mfma_f32_16x16x32_bf16 v[122:125], v[138:141], v[182:185], v[122:125]
	v_mfma_f32_16x16x32_bf16 v[110:113], v[130:133], v[190:193], v[110:113]
	v_mfma_f32_16x16x32_bf16 v[106:109], v[138:141], v[190:193], v[106:109]
	v_mfma_f32_16x16x32_bf16 v[94:97], v[130:133], v[202:205], v[94:97]
	v_mfma_f32_16x16x32_bf16 v[90:93], v[138:141], v[202:205], v[90:93]
	v_mfma_f32_16x16x32_bf16 v[78:81], v[130:133], v[210:213], v[78:81]
	v_mfma_f32_16x16x32_bf16 v[74:77], v[138:141], v[210:213], v[74:77]
	v_mfma_f32_16x16x32_bf16 v[118:121], v[134:137], v[186:189], v[118:121]
	v_mfma_f32_16x16x32_bf16 v[122:125], v[142:145], v[186:189], v[122:125]
	v_mfma_f32_16x16x32_bf16 v[110:113], v[134:137], v[194:197], v[110:113]
	v_mfma_f32_16x16x32_bf16 v[106:109], v[142:145], v[194:197], v[106:109]
	v_mfma_f32_16x16x32_bf16 v[94:97], v[134:137], v[206:209], v[94:97]
	v_mfma_f32_16x16x32_bf16 v[90:93], v[142:145], v[206:209], v[90:93]
	v_mfma_f32_16x16x32_bf16 v[78:81], v[134:137], v[214:217], v[78:81]
	v_mfma_f32_16x16x32_bf16 v[74:77], v[142:145], v[214:217], v[74:77]
	v_mfma_f32_16x16x32_bf16 v[126:129], v[146:149], v[182:185], v[126:129]
	v_mfma_f32_16x16x32_bf16 v[114:117], v[174:177], v[182:185], v[114:117]
	v_mfma_f32_16x16x32_bf16 v[102:105], v[146:149], v[190:193], v[102:105]
	v_mfma_f32_16x16x32_bf16 v[98:101], v[174:177], v[190:193], v[98:101]
	v_mfma_f32_16x16x32_bf16 v[86:89], v[146:149], v[202:205], v[86:89]
	v_mfma_f32_16x16x32_bf16 v[82:85], v[174:177], v[202:205], v[82:85]
	v_mfma_f32_16x16x32_bf16 v[70:73], v[146:149], v[210:213], v[70:73]
	v_mfma_f32_16x16x32_bf16 v[66:69], v[174:177], v[210:213], v[66:69]
	v_mfma_f32_16x16x32_bf16 v[126:129], v[150:153], v[186:189], v[126:129]
	v_mfma_f32_16x16x32_bf16 v[114:117], v[178:181], v[186:189], v[114:117]
	v_mfma_f32_16x16x32_bf16 v[102:105], v[150:153], v[194:197], v[102:105]
	v_mfma_f32_16x16x32_bf16 v[98:101], v[178:181], v[194:197], v[98:101]
	v_mfma_f32_16x16x32_bf16 v[86:89], v[150:153], v[206:209], v[86:89]
	v_mfma_f32_16x16x32_bf16 v[82:85], v[178:181], v[206:209], v[82:85]
	v_mfma_f32_16x16x32_bf16 v[70:73], v[150:153], v[214:217], v[70:73]
	v_mfma_f32_16x16x32_bf16 v[66:69], v[178:181], v[214:217], v[66:69]
	s_barrier
	s_add_i32 s50, s78, s41
	v_lshl_add_u64 v[218:219], v[218:219], 0, s[14:15]
	s_mov_b32 m0, s50
	ds_read_b128 v[182:185], v200 offset:49152
	ds_read_b128 v[186:189], v200 offset:50176
	ds_read_b128 v[190:193], v200 offset:51200
	ds_read_b128 v[194:197], v200 offset:52224
	ds_read_b128 v[202:205], v200 offset:53248
	ds_read_b128 v[206:209], v200 offset:54272
	ds_read_b128 v[210:213], v200 offset:55296
	ds_read_b128 v[214:217], v200 offset:56320
	global_load_lds_dwordx4 v[218:219], off
	s_add_i32 m0, s50, 0x2000
	s_add_u32 s50, s54, 0x20080
	v_lshl_add_u64 v[218:219], v[220:221], 0, s[14:15]
	s_addc_u32 s51, s55, 0
	s_add_i32 s54, s79, s41
	global_load_lds_dwordx4 v[218:219], off
	v_lshl_add_u64 v[218:219], s[50:51], 0, v[156:157]
	s_mov_b32 m0, s54
	s_nop 0
	global_load_lds_dwordx4 v[218:219], off
	v_lshl_add_u64 v[218:219], s[50:51], 0, v[160:161]
	s_add_i32 m0, s54, 0x2000
	s_nop 0
	global_load_lds_dwordx4 v[218:219], off
	v_lshl_add_u64 v[218:219], s[52:53], 0, v[154:155]
	s_mov_b32 m0, s69
	s_nop 0
	global_load_lds_dwordx4 v[218:219], off
	v_lshl_add_u64 v[218:219], s[52:53], 0, v[158:159]
	s_mov_b32 m0, s70
	s_nop 0
	global_load_lds_dwordx4 v[218:219], off
	s_nop 0
	s_nop 0
	s_nop 0
	s_waitcnt vmcnt(8)
	s_waitcnt lgkmcnt(0)
	s_barrier
	v_mfma_f32_16x16x32_bf16 v[62:65], v[130:133], v[182:185], v[62:65]
	v_mfma_f32_16x16x32_bf16 v[58:61], v[138:141], v[182:185], v[58:61]
	v_mfma_f32_16x16x32_bf16 v[46:49], v[130:133], v[190:193], v[46:49]
	v_mfma_f32_16x16x32_bf16 v[42:45], v[138:141], v[190:193], v[42:45]
	v_mfma_f32_16x16x32_bf16 v[30:33], v[130:133], v[202:205], v[30:33]
	v_mfma_f32_16x16x32_bf16 v[26:29], v[138:141], v[202:205], v[26:29]
	v_mfma_f32_16x16x32_bf16 v[14:17], v[130:133], v[210:213], v[14:17]
	v_mfma_f32_16x16x32_bf16 v[10:13], v[138:141], v[210:213], v[10:13]
	v_mfma_f32_16x16x32_bf16 v[62:65], v[134:137], v[186:189], v[62:65]
	v_mfma_f32_16x16x32_bf16 v[58:61], v[142:145], v[186:189], v[58:61]
	v_mfma_f32_16x16x32_bf16 v[46:49], v[134:137], v[194:197], v[46:49]
	v_mfma_f32_16x16x32_bf16 v[42:45], v[142:145], v[194:197], v[42:45]
	v_mfma_f32_16x16x32_bf16 v[30:33], v[134:137], v[206:209], v[30:33]
	v_mfma_f32_16x16x32_bf16 v[26:29], v[142:145], v[206:209], v[26:29]
	v_mfma_f32_16x16x32_bf16 v[14:17], v[134:137], v[214:217], v[14:17]
	v_mfma_f32_16x16x32_bf16 v[10:13], v[142:145], v[214:217], v[10:13]
	v_mfma_f32_16x16x32_bf16 v[54:57], v[146:149], v[182:185], v[54:57]
	v_mfma_f32_16x16x32_bf16 v[50:53], v[174:177], v[182:185], v[50:53]
	v_mfma_f32_16x16x32_bf16 v[38:41], v[146:149], v[190:193], v[38:41]
	v_mfma_f32_16x16x32_bf16 v[34:37], v[174:177], v[190:193], v[34:37]
	v_mfma_f32_16x16x32_bf16 v[22:25], v[146:149], v[202:205], v[22:25]
	v_mfma_f32_16x16x32_bf16 v[18:21], v[174:177], v[202:205], v[18:21]
	v_mfma_f32_16x16x32_bf16 v[6:9], v[146:149], v[210:213], v[6:9]
	v_mfma_f32_16x16x32_bf16 v[2:5], v[174:177], v[210:213], v[2:5]
	v_mfma_f32_16x16x32_bf16 v[54:57], v[150:153], v[186:189], v[54:57]
	v_mfma_f32_16x16x32_bf16 v[50:53], v[178:181], v[186:189], v[50:53]
	v_mfma_f32_16x16x32_bf16 v[38:41], v[150:153], v[194:197], v[38:41]
	v_mfma_f32_16x16x32_bf16 v[34:37], v[178:181], v[194:197], v[34:37]
	v_mfma_f32_16x16x32_bf16 v[22:25], v[150:153], v[206:209], v[22:25]
	v_mfma_f32_16x16x32_bf16 v[18:21], v[178:181], v[206:209], v[18:21]
	v_mfma_f32_16x16x32_bf16 v[6:9], v[150:153], v[214:217], v[6:9]
	v_mfma_f32_16x16x32_bf16 v[2:5], v[178:181], v[214:217], v[2:5]
	s_barrier
	s_add_u32 s23, s23, 0x100
	s_addc_u32 s25, s25, 0
	s_add_u32 s34, s34, 0x800000
	s_addc_u32 s35, s35, 0
	s_cmp_ge_i32 s31, s67
	s_mov_b32 s52, s31
	s_cbranch_scc0 .LBB0_599

.LBB0_740:
	v_add_u32_e32 v144, s88, v188
	v_add_u32_e32 v160, s89, v188
	ds_read_b128 v[132:135], v144
	ds_read_b128 v[136:139], v144 offset:1024
	ds_read_b128 v[140:143], v144 offset:2048
	ds_read_b128 v[144:147], v144 offset:3072
	ds_read_b128 v[148:151], v160
	ds_read_b128 v[152:155], v160 offset:1024
	ds_read_b128 v[156:159], v160 offset:2048
	ds_read_b128 v[184:187], v160 offset:3072
	s_add_i32 s92, s55, 2
	s_add_u32 s50, s60, 0x3fc000
	s_addc_u32 s51, s61, 0
	s_cmp_eq_u32 s87, s55
	s_cselect_b32 s70, s64, s50
	s_cselect_b32 s71, s65, s51
	s_cselect_b32 s69, s67, s53
	s_cselect_b32 s68, s66, s13
	s_add_u32 s62, s70, 0x400000
	s_addc_u32 s63, s71, 0
	v_lshl_add_u64 v[160:161], s[60:61], 0, v[176:177]
	s_add_i32 m0, s77, 0xc000
	ds_read_b128 v[192:195], v189
	ds_read_b128 v[196:199], v189 offset:1024
	ds_read_b128 v[200:203], v189 offset:2048
	ds_read_b128 v[204:207], v189 offset:3072
	ds_read_b128 v[208:211], v189 offset:4096
	ds_read_b128 v[212:215], v189 offset:5120
	ds_read_b128 v[216:219], v189 offset:6144
	ds_read_b128 v[220:223], v189 offset:7168
	global_load_lds_dwordx4 v[160:161], off
	v_lshl_add_u64 v[160:161], s[60:61], 0, v[178:179]
	s_add_i32 m0, s77, 0xe000
	s_nop 0
	global_load_lds_dwordx4 v[160:161], off
	s_nop 0
	s_waitcnt vmcnt(8)
	s_waitcnt lgkmcnt(0)
	s_barrier
	v_mfma_f32_16x16x32_bf16 v[30:33], v[132:135], v[192:195], v[30:33]
	v_mfma_f32_16x16x32_bf16 v[26:29], v[140:143], v[192:195], v[26:29]
	v_mfma_f32_16x16x32_bf16 v[86:89], v[132:135], v[200:203], v[86:89]
	v_mfma_f32_16x16x32_bf16 v[66:69], v[140:143], v[200:203], v[66:69]
	v_mfma_f32_16x16x32_bf16 v[94:97], v[132:135], v[208:211], v[94:97]
	v_mfma_f32_16x16x32_bf16 v[82:85], v[140:143], v[208:211], v[82:85]
	v_mfma_f32_16x16x32_bf16 v[90:93], v[132:135], v[216:219], v[90:93]
	v_mfma_f32_16x16x32_bf16 v[78:81], v[140:143], v[216:219], v[78:81]
	v_mfma_f32_16x16x32_bf16 v[30:33], v[136:139], v[196:199], v[30:33]
	v_mfma_f32_16x16x32_bf16 v[26:29], v[144:147], v[196:199], v[26:29]
	v_mfma_f32_16x16x32_bf16 v[86:89], v[136:139], v[204:207], v[86:89]
	v_mfma_f32_16x16x32_bf16 v[66:69], v[144:147], v[204:207], v[66:69]
	v_mfma_f32_16x16x32_bf16 v[94:97], v[136:139], v[212:215], v[94:97]
	v_mfma_f32_16x16x32_bf16 v[82:85], v[144:147], v[212:215], v[82:85]
	v_mfma_f32_16x16x32_bf16 v[90:93], v[136:139], v[220:223], v[90:93]
	v_mfma_f32_16x16x32_bf16 v[78:81], v[144:147], v[220:223], v[78:81]
	v_mfma_f32_16x16x32_bf16 v[50:53], v[148:151], v[192:195], v[50:53]
	v_mfma_f32_16x16x32_bf16 v[42:45], v[156:159], v[192:195], v[42:45]
	v_mfma_f32_16x16x32_bf16 v[14:17], v[148:151], v[200:203], v[14:17]
	v_mfma_f32_16x16x32_bf16 v[2:5], v[156:159], v[200:203], v[2:5]
	v_mfma_f32_16x16x32_bf16 v[22:25], v[148:151], v[208:211], v[22:25]
	v_mfma_f32_16x16x32_bf16 v[10:13], v[156:159], v[208:211], v[10:13]
	v_mfma_f32_16x16x32_bf16 v[18:21], v[148:151], v[216:219], v[18:21]
	v_mfma_f32_16x16x32_bf16 v[6:9], v[156:159], v[216:219], v[6:9]
	v_mfma_f32_16x16x32_bf16 v[50:53], v[152:155], v[196:199], v[50:53]
	v_mfma_f32_16x16x32_bf16 v[42:45], v[184:187], v[196:199], v[42:45]
	v_mfma_f32_16x16x32_bf16 v[14:17], v[152:155], v[204:207], v[14:17]
	v_mfma_f32_16x16x32_bf16 v[2:5], v[184:187], v[204:207], v[2:5]
	v_mfma_f32_16x16x32_bf16 v[22:25], v[152:155], v[212:215], v[22:25]
	v_mfma_f32_16x16x32_bf16 v[10:13], v[184:187], v[212:215], v[10:13]
	v_mfma_f32_16x16x32_bf16 v[18:21], v[152:155], v[220:223], v[18:21]
	v_mfma_f32_16x16x32_bf16 v[6:9], v[184:187], v[220:223], v[6:9]
	s_barrier
	s_add_i32 s50, s88, s76
	v_lshl_add_u64 v[160:161], s[68:69], 0, v[164:165]
	s_mov_b32 m0, s50
	ds_read_b128 v[192:195], v189 offset:16384
	ds_read_b128 v[196:199], v189 offset:17408
	ds_read_b128 v[200:203], v189 offset:18432
	ds_read_b128 v[204:207], v189 offset:19456
	ds_read_b128 v[208:211], v189 offset:20480
	ds_read_b128 v[212:215], v189 offset:21504
	ds_read_b128 v[216:219], v189 offset:22528
	ds_read_b128 v[220:223], v189 offset:23552
	global_load_lds_dwordx4 v[160:161], off
	s_add_i32 m0, s50, 0x2000
	s_add_u32 s50, s68, 0x10000
	v_lshl_add_u64 v[224:225], s[68:69], 0, v[168:169]
	s_addc_u32 s51, s69, 0
	s_add_i32 s55, s89, s76
	global_load_lds_dwordx4 v[224:225], off
	v_lshl_add_u64 v[226:227], s[50:51], 0, v[164:165]
	s_mov_b32 m0, s55
	s_nop 0
	global_load_lds_dwordx4 v[226:227], off
	v_lshl_add_u64 v[226:227], s[50:51], 0, v[168:169]
	s_add_i32 m0, s55, 0x2000
	s_nop 0
	global_load_lds_dwordx4 v[226:227], off
	v_lshl_add_u64 v[226:227], s[70:71], 0, v[162:163]
	s_mov_b32 m0, s77
	s_nop 0
	global_load_lds_dwordx4 v[226:227], off
	v_lshl_add_u64 v[226:227], s[70:71], 0, v[166:167]
	s_mov_b32 m0, s78
	s_nop 0
	global_load_lds_dwordx4 v[226:227], off
	s_nop 0
	s_nop 0
	s_nop 0
	s_waitcnt vmcnt(8)
	s_waitcnt lgkmcnt(0)
	s_barrier
	v_mfma_f32_16x16x32_bf16 v[118:121], v[132:135], v[192:195], v[118:121]
	v_mfma_f32_16x16x32_bf16 v[102:105], v[140:143], v[192:195], v[102:105]
	v_mfma_f32_16x16x32_bf16 v[114:117], v[132:135], v[200:203], v[114:117]
	v_mfma_f32_16x16x32_bf16 v[98:101], v[140:143], v[200:203], v[98:101]
	v_mfma_f32_16x16x32_bf16 v[126:129], v[132:135], v[208:211], v[126:129]
	v_mfma_f32_16x16x32_bf16 v[110:113], v[140:143], v[208:211], v[110:113]
	v_mfma_f32_16x16x32_bf16 v[122:125], v[132:135], v[216:219], v[122:125]
	v_mfma_f32_16x16x32_bf16 v[106:109], v[140:143], v[216:219], v[106:109]
	v_mfma_f32_16x16x32_bf16 v[118:121], v[136:139], v[196:199], v[118:121]
	v_mfma_f32_16x16x32_bf16 v[102:105], v[144:147], v[196:199], v[102:105]
	v_mfma_f32_16x16x32_bf16 v[114:117], v[136:139], v[204:207], v[114:117]
	v_mfma_f32_16x16x32_bf16 v[98:101], v[144:147], v[204:207], v[98:101]
	v_mfma_f32_16x16x32_bf16 v[126:129], v[136:139], v[212:215], v[126:129]
	v_mfma_f32_16x16x32_bf16 v[110:113], v[144:147], v[212:215], v[110:113]
	v_mfma_f32_16x16x32_bf16 v[122:125], v[136:139], v[220:223], v[122:125]
	v_mfma_f32_16x16x32_bf16 v[106:109], v[144:147], v[220:223], v[106:109]
	v_mfma_f32_16x16x32_bf16 v[62:65], v[148:151], v[192:195], v[62:65]
	v_mfma_f32_16x16x32_bf16 v[38:41], v[156:159], v[192:195], v[38:41]
	v_mfma_f32_16x16x32_bf16 v[58:61], v[148:151], v[200:203], v[58:61]
	v_mfma_f32_16x16x32_bf16 v[34:37], v[156:159], v[200:203], v[34:37]
	v_mfma_f32_16x16x32_bf16 v[74:77], v[148:151], v[208:211], v[74:77]
	v_mfma_f32_16x16x32_bf16 v[54:57], v[156:159], v[208:211], v[54:57]
	v_mfma_f32_16x16x32_bf16 v[70:73], v[148:151], v[216:219], v[70:73]
	v_mfma_f32_16x16x32_bf16 v[46:49], v[156:159], v[216:219], v[46:49]
	v_mfma_f32_16x16x32_bf16 v[62:65], v[152:155], v[196:199], v[62:65]
	v_mfma_f32_16x16x32_bf16 v[38:41], v[184:187], v[196:199], v[38:41]
	v_mfma_f32_16x16x32_bf16 v[58:61], v[152:155], v[204:207], v[58:61]
	v_mfma_f32_16x16x32_bf16 v[34:37], v[184:187], v[204:207], v[34:37]
	v_mfma_f32_16x16x32_bf16 v[74:77], v[152:155], v[212:215], v[74:77]
	v_mfma_f32_16x16x32_bf16 v[54:57], v[184:187], v[212:215], v[54:57]
	v_mfma_f32_16x16x32_bf16 v[70:73], v[152:155], v[220:223], v[70:73]
	v_mfma_f32_16x16x32_bf16 v[46:49], v[184:187], v[220:223], v[46:49]
	s_barrier
	s_add_i32 s55, 0, 0x18000
	s_add_i32 s93, 0, 0x1c000
	v_add_u32_e32 v144, s55, v188
	v_add_u32_e32 v184, s93, v188
	ds_read_b128 v[132:135], v144
	ds_read_b128 v[136:139], v144 offset:1024
	ds_read_b128 v[140:143], v144 offset:2048
	ds_read_b128 v[144:147], v144 offset:3072
	ds_read_b128 v[148:151], v184
	ds_read_b128 v[152:155], v184 offset:1024
	ds_read_b128 v[156:159], v184 offset:2048
	ds_read_b128 v[184:187], v184 offset:3072
	s_add_u32 s50, s70, 0x4000
	s_addc_u32 s51, s71, 0
	s_mov_b32 m0, s79
	v_lshl_add_u64 v[226:227], s[50:51], 0, v[162:163]
	ds_read_b128 v[192:195], v189 offset:32768
	ds_read_b128 v[196:199], v189 offset:33792
	ds_read_b128 v[200:203], v189 offset:34816
	ds_read_b128 v[204:207], v189 offset:35840
	ds_read_b128 v[208:211], v189 offset:36864
	ds_read_b128 v[212:215], v189 offset:37888
	ds_read_b128 v[216:219], v189 offset:38912
	ds_read_b128 v[220:223], v189 offset:39936
	global_load_lds_dwordx4 v[226:227], off
	v_lshl_add_u64 v[226:227], s[50:51], 0, v[166:167]
	s_mov_b32 m0, s80
	s_nop 0
	global_load_lds_dwordx4 v[226:227], off
	s_nop 0
	s_nop 0
	s_nop 0
	s_nop 0
	s_nop 0
	s_nop 0
	s_nop 0
	s_nop 0
	s_waitcnt vmcnt(8)
	s_waitcnt lgkmcnt(0)
	s_barrier
	v_mfma_f32_16x16x32_bf16 v[30:33], v[132:135], v[192:195], v[30:33]
	v_mfma_f32_16x16x32_bf16 v[26:29], v[140:143], v[192:195], v[26:29]
	v_mfma_f32_16x16x32_bf16 v[86:89], v[132:135], v[200:203], v[86:89]
	v_mfma_f32_16x16x32_bf16 v[66:69], v[140:143], v[200:203], v[66:69]
	v_mfma_f32_16x16x32_bf16 v[94:97], v[132:135], v[208:211], v[94:97]
	v_mfma_f32_16x16x32_bf16 v[82:85], v[140:143], v[208:211], v[82:85]
	v_mfma_f32_16x16x32_bf16 v[90:93], v[132:135], v[216:219], v[90:93]
	v_mfma_f32_16x16x32_bf16 v[78:81], v[140:143], v[216:219], v[78:81]
	v_mfma_f32_16x16x32_bf16 v[30:33], v[136:139], v[196:199], v[30:33]
	v_mfma_f32_16x16x32_bf16 v[26:29], v[144:147], v[196:199], v[26:29]
	v_mfma_f32_16x16x32_bf16 v[86:89], v[136:139], v[204:207], v[86:89]
	v_mfma_f32_16x16x32_bf16 v[66:69], v[144:147], v[204:207], v[66:69]
	v_mfma_f32_16x16x32_bf16 v[94:97], v[136:139], v[212:215], v[94:97]
	v_mfma_f32_16x16x32_bf16 v[82:85], v[144:147], v[212:215], v[82:85]
	v_mfma_f32_16x16x32_bf16 v[90:93], v[136:139], v[220:223], v[90:93]
	v_mfma_f32_16x16x32_bf16 v[78:81], v[144:147], v[220:223], v[78:81]
	v_mfma_f32_16x16x32_bf16 v[50:53], v[148:151], v[192:195], v[50:53]
	v_mfma_f32_16x16x32_bf16 v[42:45], v[156:159], v[192:195], v[42:45]
	v_mfma_f32_16x16x32_bf16 v[14:17], v[148:151], v[200:203], v[14:17]
	v_mfma_f32_16x16x32_bf16 v[2:5], v[156:159], v[200:203], v[2:5]
	v_mfma_f32_16x16x32_bf16 v[22:25], v[148:151], v[208:211], v[22:25]
	v_mfma_f32_16x16x32_bf16 v[10:13], v[156:159], v[208:211], v[10:13]
	v_mfma_f32_16x16x32_bf16 v[18:21], v[148:151], v[216:219], v[18:21]
	v_mfma_f32_16x16x32_bf16 v[6:9], v[156:159], v[216:219], v[6:9]
	v_mfma_f32_16x16x32_bf16 v[50:53], v[152:155], v[196:199], v[50:53]
	v_mfma_f32_16x16x32_bf16 v[42:45], v[184:187], v[196:199], v[42:45]
	v_mfma_f32_16x16x32_bf16 v[14:17], v[152:155], v[204:207], v[14:17]
	v_mfma_f32_16x16x32_bf16 v[2:5], v[184:187], v[204:207], v[2:5]
	v_mfma_f32_16x16x32_bf16 v[22:25], v[152:155], v[212:215], v[22:25]
	v_mfma_f32_16x16x32_bf16 v[10:13], v[184:187], v[212:215], v[10:13]
	v_mfma_f32_16x16x32_bf16 v[18:21], v[152:155], v[220:223], v[18:21]
	v_mfma_f32_16x16x32_bf16 v[6:9], v[184:187], v[220:223], v[6:9]
	s_barrier
	s_add_i32 s50, s55, s76
	v_lshl_add_u64 v[160:161], v[160:161], 0, s[14:15]
	s_mov_b32 m0, s50
	ds_read_b128 v[192:195], v189 offset:49152
	ds_read_b128 v[196:199], v189 offset:50176
	ds_read_b128 v[200:203], v189 offset:51200
	ds_read_b128 v[204:207], v189 offset:52224
	ds_read_b128 v[208:211], v189 offset:53248
	ds_read_b128 v[212:215], v189 offset:54272
	ds_read_b128 v[216:219], v189 offset:55296
	ds_read_b128 v[220:223], v189 offset:56320
	global_load_lds_dwordx4 v[160:161], off
	s_add_i32 m0, s50, 0x2000
	s_add_u32 s50, s68, 0x10080
	v_lshl_add_u64 v[160:161], v[224:225], 0, s[14:15]
	s_addc_u32 s51, s69, 0
	s_add_i32 s55, s93, s76
	global_load_lds_dwordx4 v[160:161], off
	v_lshl_add_u64 v[160:161], s[50:51], 0, v[164:165]
	s_mov_b32 m0, s55
	s_nop 0
	global_load_lds_dwordx4 v[160:161], off
	v_lshl_add_u64 v[160:161], s[50:51], 0, v[168:169]
	s_add_i32 m0, s55, 0x2000
	s_nop 0
	global_load_lds_dwordx4 v[160:161], off
	v_lshl_add_u64 v[160:161], s[62:63], 0, v[162:163]
	s_mov_b32 m0, s84
	s_nop 0
	global_load_lds_dwordx4 v[160:161], off
	v_lshl_add_u64 v[160:161], s[62:63], 0, v[166:167]
	s_mov_b32 m0, s85
	s_nop 0
	global_load_lds_dwordx4 v[160:161], off
	s_nop 0
	s_nop 0
	s_nop 0
	s_waitcnt vmcnt(8)
	s_waitcnt lgkmcnt(0)
	s_barrier
	v_mfma_f32_16x16x32_bf16 v[118:121], v[132:135], v[192:195], v[118:121]
	v_mfma_f32_16x16x32_bf16 v[102:105], v[140:143], v[192:195], v[102:105]
	v_mfma_f32_16x16x32_bf16 v[114:117], v[132:135], v[200:203], v[114:117]
	v_mfma_f32_16x16x32_bf16 v[98:101], v[140:143], v[200:203], v[98:101]
	v_mfma_f32_16x16x32_bf16 v[126:129], v[132:135], v[208:211], v[126:129]
	v_mfma_f32_16x16x32_bf16 v[110:113], v[140:143], v[208:211], v[110:113]
	v_mfma_f32_16x16x32_bf16 v[122:125], v[132:135], v[216:219], v[122:125]
	v_mfma_f32_16x16x32_bf16 v[106:109], v[140:143], v[216:219], v[106:109]
	v_mfma_f32_16x16x32_bf16 v[118:121], v[136:139], v[196:199], v[118:121]
	v_mfma_f32_16x16x32_bf16 v[102:105], v[144:147], v[196:199], v[102:105]
	v_mfma_f32_16x16x32_bf16 v[114:117], v[136:139], v[204:207], v[114:117]
	v_mfma_f32_16x16x32_bf16 v[98:101], v[144:147], v[204:207], v[98:101]
	v_mfma_f32_16x16x32_bf16 v[126:129], v[136:139], v[212:215], v[126:129]
	v_mfma_f32_16x16x32_bf16 v[110:113], v[144:147], v[212:215], v[110:113]
	v_mfma_f32_16x16x32_bf16 v[122:125], v[136:139], v[220:223], v[122:125]
	v_mfma_f32_16x16x32_bf16 v[106:109], v[144:147], v[220:223], v[106:109]
	v_mfma_f32_16x16x32_bf16 v[62:65], v[148:151], v[192:195], v[62:65]
	v_mfma_f32_16x16x32_bf16 v[38:41], v[156:159], v[192:195], v[38:41]
	v_mfma_f32_16x16x32_bf16 v[58:61], v[148:151], v[200:203], v[58:61]
	v_mfma_f32_16x16x32_bf16 v[34:37], v[156:159], v[200:203], v[34:37]
	v_mfma_f32_16x16x32_bf16 v[74:77], v[148:151], v[208:211], v[74:77]
	v_mfma_f32_16x16x32_bf16 v[54:57], v[156:159], v[208:211], v[54:57]
	v_mfma_f32_16x16x32_bf16 v[70:73], v[148:151], v[216:219], v[70:73]
	v_mfma_f32_16x16x32_bf16 v[46:49], v[156:159], v[216:219], v[46:49]
	v_mfma_f32_16x16x32_bf16 v[62:65], v[152:155], v[196:199], v[62:65]
	v_mfma_f32_16x16x32_bf16 v[38:41], v[184:187], v[196:199], v[38:41]
	v_mfma_f32_16x16x32_bf16 v[58:61], v[152:155], v[204:207], v[58:61]
	v_mfma_f32_16x16x32_bf16 v[34:37], v[184:187], v[204:207], v[34:37]
	v_mfma_f32_16x16x32_bf16 v[74:77], v[152:155], v[212:215], v[74:77]
	v_mfma_f32_16x16x32_bf16 v[54:57], v[184:187], v[212:215], v[54:57]
	v_mfma_f32_16x16x32_bf16 v[70:73], v[152:155], v[220:223], v[70:73]
	v_mfma_f32_16x16x32_bf16 v[46:49], v[184:187], v[220:223], v[46:49]
	s_barrier
	s_add_u32 s13, s13, 0x100
	s_addc_u32 s53, s53, 0
	s_add_u32 s60, s60, 0x800000
	s_addc_u32 s61, s61, 0
	s_cmp_ge_i32 s92, s83
	s_cbranch_scc0 .LBB0_738

.LBB0_872:
	v_add_u32_e32 v162, s73, v140
	v_add_u32_e32 v178, s74, v140
	ds_read_b128 v[150:153], v162
	ds_read_b128 v[154:157], v162 offset:1024
	ds_read_b128 v[158:161], v162 offset:2048
	ds_read_b128 v[162:165], v162 offset:3072
	ds_read_b128 v[166:169], v178
	ds_read_b128 v[170:173], v178 offset:1024
	ds_read_b128 v[174:177], v178 offset:2048
	ds_read_b128 v[178:181], v178 offset:3072
	s_add_i32 s77, s52, 2
	s_add_u32 s50, s34, 0xfffc0080
	s_addc_u32 s51, s35, -1
	s_cmp_eq_u32 s70, s52
	s_cselect_b32 s52, s30, s21
	s_cselect_b32 s55, s29, s51
	s_cselect_b32 s54, s28, s50
	s_cselect_b32 s53, s31, s23
	v_lshl_add_u64 v[214:215], s[34:35], 0, v[132:133]
	s_add_i32 m0, s60, 0xc000
	ds_read_b128 v[182:185], v149
	ds_read_b128 v[186:189], v149 offset:1024
	ds_read_b128 v[190:193], v149 offset:2048
	ds_read_b128 v[194:197], v149 offset:3072
	ds_read_b128 v[198:201], v149 offset:4096
	ds_read_b128 v[202:205], v149 offset:5120
	ds_read_b128 v[206:209], v149 offset:6144
	ds_read_b128 v[210:213], v149 offset:7168
	global_load_lds_dwordx4 v[214:215], off
	v_lshl_add_u64 v[214:215], s[34:35], 0, v[134:135]
	s_add_i32 m0, s60, 0xe000
	s_nop 0
	global_load_lds_dwordx4 v[214:215], off
	s_waitcnt vmcnt(8)
	s_waitcnt lgkmcnt(0)
	s_barrier
	v_mfma_f32_16x16x32_bf16 v[78:81], v[150:153], v[182:185], v[78:81]
	v_mfma_f32_16x16x32_bf16 v[14:17], v[158:161], v[182:185], v[14:17]
	v_mfma_f32_16x16x32_bf16 v[66:69], v[150:153], v[190:193], v[66:69]
	v_mfma_f32_16x16x32_bf16 v[2:5], v[158:161], v[190:193], v[2:5]
	v_mfma_f32_16x16x32_bf16 v[70:73], v[150:153], v[198:201], v[70:73]
	v_mfma_f32_16x16x32_bf16 v[6:9], v[158:161], v[198:201], v[6:9]
	v_mfma_f32_16x16x32_bf16 v[74:77], v[150:153], v[206:209], v[74:77]
	v_mfma_f32_16x16x32_bf16 v[10:13], v[158:161], v[206:209], v[10:13]
	v_mfma_f32_16x16x32_bf16 v[78:81], v[154:157], v[186:189], v[78:81]
	v_mfma_f32_16x16x32_bf16 v[14:17], v[162:165], v[186:189], v[14:17]
	v_mfma_f32_16x16x32_bf16 v[66:69], v[154:157], v[194:197], v[66:69]
	v_mfma_f32_16x16x32_bf16 v[2:5], v[162:165], v[194:197], v[2:5]
	v_mfma_f32_16x16x32_bf16 v[70:73], v[154:157], v[202:205], v[70:73]
	v_mfma_f32_16x16x32_bf16 v[6:9], v[162:165], v[202:205], v[6:9]
	v_mfma_f32_16x16x32_bf16 v[74:77], v[154:157], v[210:213], v[74:77]
	v_mfma_f32_16x16x32_bf16 v[10:13], v[162:165], v[210:213], v[10:13]
	v_mfma_f32_16x16x32_bf16 v[98:101], v[166:169], v[182:185], v[98:101]
	v_mfma_f32_16x16x32_bf16 v[34:37], v[174:177], v[182:185], v[34:37]
	v_mfma_f32_16x16x32_bf16 v[82:85], v[166:169], v[190:193], v[82:85]
	v_mfma_f32_16x16x32_bf16 v[18:21], v[174:177], v[190:193], v[18:21]
	v_mfma_f32_16x16x32_bf16 v[86:89], v[166:169], v[198:201], v[86:89]
	v_mfma_f32_16x16x32_bf16 v[22:25], v[174:177], v[198:201], v[22:25]
	v_mfma_f32_16x16x32_bf16 v[94:97], v[166:169], v[206:209], v[94:97]
	v_mfma_f32_16x16x32_bf16 v[30:33], v[174:177], v[206:209], v[30:33]
	v_mfma_f32_16x16x32_bf16 v[98:101], v[170:173], v[186:189], v[98:101]
	v_mfma_f32_16x16x32_bf16 v[34:37], v[178:181], v[186:189], v[34:37]
	v_mfma_f32_16x16x32_bf16 v[82:85], v[170:173], v[194:197], v[82:85]
	v_mfma_f32_16x16x32_bf16 v[18:21], v[178:181], v[194:197], v[18:21]
	v_mfma_f32_16x16x32_bf16 v[86:89], v[170:173], v[202:205], v[86:89]
	v_mfma_f32_16x16x32_bf16 v[22:25], v[178:181], v[202:205], v[22:25]
	v_mfma_f32_16x16x32_bf16 v[94:97], v[170:173], v[210:213], v[94:97]
	v_mfma_f32_16x16x32_bf16 v[30:33], v[178:181], v[210:213], v[30:33]
	s_barrier
	s_add_i32 s50, s73, s15
	v_lshl_add_u64 v[214:215], s[52:53], 0, v[228:229]
	s_mov_b32 m0, s50
	ds_read_b128 v[182:185], v149 offset:16384
	ds_read_b128 v[186:189], v149 offset:17408
	ds_read_b128 v[190:193], v149 offset:18432
	ds_read_b128 v[194:197], v149 offset:19456
	ds_read_b128 v[198:201], v149 offset:20480
	ds_read_b128 v[202:205], v149 offset:21504
	ds_read_b128 v[206:209], v149 offset:22528
	ds_read_b128 v[210:213], v149 offset:23552
	global_load_lds_dwordx4 v[214:215], off
	s_add_i32 m0, s50, 0x2000
	s_add_u32 s50, s52, 0x40000
	v_lshl_add_u64 v[216:217], s[52:53], 0, v[232:233]
	s_addc_u32 s51, s53, 0
	s_add_i32 s78, s74, s15
	global_load_lds_dwordx4 v[216:217], off
	v_lshl_add_u64 v[218:219], s[50:51], 0, v[228:229]
	s_mov_b32 m0, s78
	v_lshl_add_u64 v[220:221], s[54:55], 0, v[230:231]
	global_load_lds_dwordx4 v[218:219], off
	v_lshl_add_u64 v[218:219], s[50:51], 0, v[232:233]
	s_add_i32 m0, s78, 0x2000
	s_nop 0
	global_load_lds_dwordx4 v[218:219], off
	v_lshl_add_u64 v[218:219], s[54:55], 0, v[226:227]
	s_mov_b32 m0, s60
	s_nop 0
	global_load_lds_dwordx4 v[218:219], off
	s_mov_b32 m0, s61
	s_nop 0
	global_load_lds_dwordx4 v[220:221], off
	s_nop 0
	s_nop 0
	s_nop 0
	s_nop 0
	s_waitcnt vmcnt(8)
	s_waitcnt lgkmcnt(0)
	s_barrier
	v_mfma_f32_16x16x32_bf16 v[90:93], v[150:153], v[182:185], v[90:93]
	v_mfma_f32_16x16x32_bf16 v[26:29], v[158:161], v[182:185], v[26:29]
	v_mfma_f32_16x16x32_bf16 v[102:105], v[150:153], v[190:193], v[102:105]
	v_mfma_f32_16x16x32_bf16 v[38:41], v[158:161], v[190:193], v[38:41]
	v_mfma_f32_16x16x32_bf16 v[106:109], v[150:153], v[198:201], v[106:109]
	v_mfma_f32_16x16x32_bf16 v[42:45], v[158:161], v[198:201], v[42:45]
	v_mfma_f32_16x16x32_bf16 v[110:113], v[150:153], v[206:209], v[110:113]
	v_mfma_f32_16x16x32_bf16 v[46:49], v[158:161], v[206:209], v[46:49]
	v_mfma_f32_16x16x32_bf16 v[90:93], v[154:157], v[186:189], v[90:93]
	v_mfma_f32_16x16x32_bf16 v[26:29], v[162:165], v[186:189], v[26:29]
	v_mfma_f32_16x16x32_bf16 v[102:105], v[154:157], v[194:197], v[102:105]
	v_mfma_f32_16x16x32_bf16 v[38:41], v[162:165], v[194:197], v[38:41]
	v_mfma_f32_16x16x32_bf16 v[106:109], v[154:157], v[202:205], v[106:109]
	v_mfma_f32_16x16x32_bf16 v[42:45], v[162:165], v[202:205], v[42:45]
	v_mfma_f32_16x16x32_bf16 v[110:113], v[154:157], v[210:213], v[110:113]
	v_mfma_f32_16x16x32_bf16 v[46:49], v[162:165], v[210:213], v[46:49]
	v_mfma_f32_16x16x32_bf16 v[114:117], v[166:169], v[182:185], v[114:117]
	v_mfma_f32_16x16x32_bf16 v[50:53], v[174:177], v[182:185], v[50:53]
	v_mfma_f32_16x16x32_bf16 v[118:121], v[166:169], v[190:193], v[118:121]
	v_mfma_f32_16x16x32_bf16 v[54:57], v[174:177], v[190:193], v[54:57]
	v_mfma_f32_16x16x32_bf16 v[122:125], v[166:169], v[198:201], v[122:125]
	v_mfma_f32_16x16x32_bf16 v[58:61], v[174:177], v[198:201], v[58:61]
	v_mfma_f32_16x16x32_bf16 v[126:129], v[166:169], v[206:209], v[126:129]
	v_mfma_f32_16x16x32_bf16 v[62:65], v[174:177], v[206:209], v[62:65]
	v_mfma_f32_16x16x32_bf16 v[114:117], v[170:173], v[186:189], v[114:117]
	v_mfma_f32_16x16x32_bf16 v[50:53], v[178:181], v[186:189], v[50:53]
	v_mfma_f32_16x16x32_bf16 v[118:121], v[170:173], v[194:197], v[118:121]
	v_mfma_f32_16x16x32_bf16 v[54:57], v[178:181], v[194:197], v[54:57]
	v_mfma_f32_16x16x32_bf16 v[122:125], v[170:173], v[202:205], v[122:125]
	v_mfma_f32_16x16x32_bf16 v[58:61], v[178:181], v[202:205], v[58:61]
	v_mfma_f32_16x16x32_bf16 v[126:129], v[170:173], v[210:213], v[126:129]
	v_mfma_f32_16x16x32_bf16 v[62:65], v[178:181], v[210:213], v[62:65]
	s_barrier
	s_add_i32 s78, 0, 0x18000
	s_add_i32 s79, 0, 0x1c000
	v_add_u32_e32 v162, s78, v140
	v_add_u32_e32 v178, s79, v140
	ds_read_b128 v[150:153], v162
	ds_read_b128 v[154:157], v162 offset:1024
	ds_read_b128 v[158:161], v162 offset:2048
	ds_read_b128 v[162:165], v162 offset:3072
	ds_read_b128 v[166:169], v178
	ds_read_b128 v[170:173], v178 offset:1024
	ds_read_b128 v[174:177], v178 offset:2048
	ds_read_b128 v[178:181], v178 offset:3072
	s_add_u32 s50, s54, 0x40000
	s_addc_u32 s51, s55, 0
	s_mov_b32 m0, s62
	v_lshl_add_u64 v[222:223], s[50:51], 0, v[226:227]
	ds_read_b128 v[182:185], v149 offset:32768
	ds_read_b128 v[186:189], v149 offset:33792
	ds_read_b128 v[190:193], v149 offset:34816
	ds_read_b128 v[194:197], v149 offset:35840
	ds_read_b128 v[198:201], v149 offset:36864
	ds_read_b128 v[202:205], v149 offset:37888
	ds_read_b128 v[206:209], v149 offset:38912
	ds_read_b128 v[210:213], v149 offset:39936
	global_load_lds_dwordx4 v[222:223], off
	v_lshl_add_u64 v[222:223], s[50:51], 0, v[230:231]
	s_mov_b32 m0, s63
	s_nop 0
	global_load_lds_dwordx4 v[222:223], off
	s_nop 0
	s_nop 0
	s_nop 0
	s_nop 0
	s_nop 0
	s_nop 0
	s_nop 0
	s_nop 0
	s_waitcnt vmcnt(8)
	s_waitcnt lgkmcnt(0)
	s_barrier
	v_mfma_f32_16x16x32_bf16 v[78:81], v[150:153], v[182:185], v[78:81]
	v_mfma_f32_16x16x32_bf16 v[14:17], v[158:161], v[182:185], v[14:17]
	v_mfma_f32_16x16x32_bf16 v[66:69], v[150:153], v[190:193], v[66:69]
	v_mfma_f32_16x16x32_bf16 v[2:5], v[158:161], v[190:193], v[2:5]
	v_mfma_f32_16x16x32_bf16 v[70:73], v[150:153], v[198:201], v[70:73]
	v_mfma_f32_16x16x32_bf16 v[6:9], v[158:161], v[198:201], v[6:9]
	v_mfma_f32_16x16x32_bf16 v[74:77], v[150:153], v[206:209], v[74:77]
	v_mfma_f32_16x16x32_bf16 v[10:13], v[158:161], v[206:209], v[10:13]
	v_mfma_f32_16x16x32_bf16 v[78:81], v[154:157], v[186:189], v[78:81]
	v_mfma_f32_16x16x32_bf16 v[14:17], v[162:165], v[186:189], v[14:17]
	v_mfma_f32_16x16x32_bf16 v[66:69], v[154:157], v[194:197], v[66:69]
	v_mfma_f32_16x16x32_bf16 v[2:5], v[162:165], v[194:197], v[2:5]
	v_mfma_f32_16x16x32_bf16 v[70:73], v[154:157], v[202:205], v[70:73]
	v_mfma_f32_16x16x32_bf16 v[6:9], v[162:165], v[202:205], v[6:9]
	v_mfma_f32_16x16x32_bf16 v[74:77], v[154:157], v[210:213], v[74:77]
	v_mfma_f32_16x16x32_bf16 v[10:13], v[162:165], v[210:213], v[10:13]
	v_mfma_f32_16x16x32_bf16 v[98:101], v[166:169], v[182:185], v[98:101]
	v_mfma_f32_16x16x32_bf16 v[34:37], v[174:177], v[182:185], v[34:37]
	v_mfma_f32_16x16x32_bf16 v[82:85], v[166:169], v[190:193], v[82:85]
	v_mfma_f32_16x16x32_bf16 v[18:21], v[174:177], v[190:193], v[18:21]
	v_mfma_f32_16x16x32_bf16 v[86:89], v[166:169], v[198:201], v[86:89]
	v_mfma_f32_16x16x32_bf16 v[22:25], v[174:177], v[198:201], v[22:25]
	v_mfma_f32_16x16x32_bf16 v[94:97], v[166:169], v[206:209], v[94:97]
	v_mfma_f32_16x16x32_bf16 v[30:33], v[174:177], v[206:209], v[30:33]
	v_mfma_f32_16x16x32_bf16 v[98:101], v[170:173], v[186:189], v[98:101]
	v_mfma_f32_16x16x32_bf16 v[34:37], v[178:181], v[186:189], v[34:37]
	v_mfma_f32_16x16x32_bf16 v[82:85], v[170:173], v[194:197], v[82:85]
	v_mfma_f32_16x16x32_bf16 v[18:21], v[178:181], v[194:197], v[18:21]
	v_mfma_f32_16x16x32_bf16 v[86:89], v[170:173], v[202:205], v[86:89]
	v_mfma_f32_16x16x32_bf16 v[22:25], v[178:181], v[202:205], v[22:25]
	v_mfma_f32_16x16x32_bf16 v[94:97], v[170:173], v[210:213], v[94:97]
	v_mfma_f32_16x16x32_bf16 v[30:33], v[178:181], v[210:213], v[30:33]
	s_barrier
	s_add_i32 s50, s78, s15
	v_lshl_add_u64 v[214:215], v[214:215], 0, s[8:9]
	s_mov_b32 m0, s50
	ds_read_b128 v[182:185], v149 offset:49152
	ds_read_b128 v[186:189], v149 offset:50176
	ds_read_b128 v[190:193], v149 offset:51200
	ds_read_b128 v[194:197], v149 offset:52224
	ds_read_b128 v[198:201], v149 offset:53248
	ds_read_b128 v[202:205], v149 offset:54272
	ds_read_b128 v[206:209], v149 offset:55296
	ds_read_b128 v[210:213], v149 offset:56320
	global_load_lds_dwordx4 v[214:215], off
	s_add_i32 m0, s50, 0x2000
	s_add_u32 s50, s52, 0x40080
	v_lshl_add_u64 v[214:215], v[216:217], 0, s[8:9]
	s_addc_u32 s51, s53, 0
	s_add_i32 s52, s79, s15
	global_load_lds_dwordx4 v[214:215], off
	v_lshl_add_u64 v[214:215], s[50:51], 0, v[228:229]
	s_mov_b32 m0, s52
	s_nop 0
	global_load_lds_dwordx4 v[214:215], off
	v_lshl_add_u64 v[214:215], s[50:51], 0, v[232:233]
	s_add_i32 m0, s52, 0x2000
	s_nop 0
	global_load_lds_dwordx4 v[214:215], off
	v_lshl_add_u64 v[214:215], v[218:219], 0, s[8:9]
	s_mov_b32 m0, s68
	s_nop 0
	global_load_lds_dwordx4 v[214:215], off
	v_lshl_add_u64 v[214:215], v[220:221], 0, s[8:9]
	s_mov_b32 m0, s69
	s_nop 0
	global_load_lds_dwordx4 v[214:215], off
	s_nop 0
	s_nop 0
	s_nop 0
	s_waitcnt vmcnt(8)
	s_waitcnt lgkmcnt(0)
	s_barrier
	v_mfma_f32_16x16x32_bf16 v[90:93], v[150:153], v[182:185], v[90:93]
	v_mfma_f32_16x16x32_bf16 v[26:29], v[158:161], v[182:185], v[26:29]
	v_mfma_f32_16x16x32_bf16 v[102:105], v[150:153], v[190:193], v[102:105]
	v_mfma_f32_16x16x32_bf16 v[38:41], v[158:161], v[190:193], v[38:41]
	v_mfma_f32_16x16x32_bf16 v[106:109], v[150:153], v[198:201], v[106:109]
	v_mfma_f32_16x16x32_bf16 v[42:45], v[158:161], v[198:201], v[42:45]
	v_mfma_f32_16x16x32_bf16 v[110:113], v[150:153], v[206:209], v[110:113]
	v_mfma_f32_16x16x32_bf16 v[46:49], v[158:161], v[206:209], v[46:49]
	v_mfma_f32_16x16x32_bf16 v[90:93], v[154:157], v[186:189], v[90:93]
	v_mfma_f32_16x16x32_bf16 v[26:29], v[162:165], v[186:189], v[26:29]
	v_mfma_f32_16x16x32_bf16 v[102:105], v[154:157], v[194:197], v[102:105]
	v_mfma_f32_16x16x32_bf16 v[38:41], v[162:165], v[194:197], v[38:41]
	v_mfma_f32_16x16x32_bf16 v[106:109], v[154:157], v[202:205], v[106:109]
	v_mfma_f32_16x16x32_bf16 v[42:45], v[162:165], v[202:205], v[42:45]
	v_mfma_f32_16x16x32_bf16 v[110:113], v[154:157], v[210:213], v[110:113]
	v_mfma_f32_16x16x32_bf16 v[46:49], v[162:165], v[210:213], v[46:49]
	v_mfma_f32_16x16x32_bf16 v[114:117], v[166:169], v[182:185], v[114:117]
	v_mfma_f32_16x16x32_bf16 v[50:53], v[174:177], v[182:185], v[50:53]
	v_mfma_f32_16x16x32_bf16 v[118:121], v[166:169], v[190:193], v[118:121]
	v_mfma_f32_16x16x32_bf16 v[54:57], v[174:177], v[190:193], v[54:57]
	v_mfma_f32_16x16x32_bf16 v[122:125], v[166:169], v[198:201], v[122:125]
	v_mfma_f32_16x16x32_bf16 v[58:61], v[174:177], v[198:201], v[58:61]
	v_mfma_f32_16x16x32_bf16 v[126:129], v[166:169], v[206:209], v[126:129]
	v_mfma_f32_16x16x32_bf16 v[62:65], v[174:177], v[206:209], v[62:65]
	v_mfma_f32_16x16x32_bf16 v[114:117], v[170:173], v[186:189], v[114:117]
	v_mfma_f32_16x16x32_bf16 v[50:53], v[178:181], v[186:189], v[50:53]
	v_mfma_f32_16x16x32_bf16 v[118:121], v[170:173], v[194:197], v[118:121]
	v_mfma_f32_16x16x32_bf16 v[54:57], v[178:181], v[194:197], v[54:57]
	v_mfma_f32_16x16x32_bf16 v[122:125], v[170:173], v[202:205], v[122:125]
	v_mfma_f32_16x16x32_bf16 v[58:61], v[178:181], v[202:205], v[58:61]
	v_mfma_f32_16x16x32_bf16 v[126:129], v[170:173], v[210:213], v[126:129]
	v_mfma_f32_16x16x32_bf16 v[62:65], v[178:181], v[210:213], v[62:65]
	s_barrier
	s_add_u32 s34, s34, 0x100
	s_addc_u32 s35, s35, 0
	s_add_u32 s21, s21, 0x100
	s_addc_u32 s23, s23, 0
	s_cmp_ge_i32 s77, s66
	s_mov_b32 s52, s77
	s_cbranch_scc0 .LBB0_872

.LBB0_1009:
	v_add_u32_e32 v0, s64, v187
	ds_read_b128 v[130:133], v0
	ds_read_b128 v[134:137], v0 offset:1024
	ds_read_b128 v[138:141], v0 offset:2048
	ds_read_b128 v[142:145], v0 offset:3072
	v_add_u32_e32 v0, s65, v187
	ds_read_b128 v[146:149], v0
	ds_read_b128 v[150:153], v0 offset:1024
	ds_read_b128 v[178:181], v0 offset:2048
	ds_read_b128 v[182:185], v0 offset:3072
	s_add_i32 s35, s42, 2
	s_add_u32 s43, s36, 0x3fc000
	s_addc_u32 s44, s37, 0
	s_cmp_eq_u32 s61, s42
	s_cselect_b32 s46, s28, s43
	s_cselect_b32 s47, s29, s44
	s_cselect_b32 s44, s30, s11
	s_cselect_b32 s45, s31, s27
	s_add_u32 s42, s46, 0x400000
	s_addc_u32 s43, s47, 0
	v_lshl_add_u64 v[0:1], s[36:37], 0, v[168:169]
	s_add_i32 m0, s51, 0xc000
	ds_read_b128 v[220:223], v215
	ds_read_b128 v[224:227], v215 offset:1024
	ds_read_b128 v[228:231], v215 offset:2048
	ds_read_b128 v[232:235], v215 offset:3072
	ds_read_b128 v[236:239], v215 offset:4096
	ds_read_b128 v[240:243], v215 offset:5120
	ds_read_b128 v[244:247], v215 offset:6144
	ds_read_b128 v[248:251], v215 offset:7168
	global_load_lds_dwordx4 v[0:1], off
	v_lshl_add_u64 v[0:1], s[36:37], 0, v[170:171]
	s_add_i32 m0, s51, 0xe000
	s_nop 0
	global_load_lds_dwordx4 v[0:1], off
	s_nop 0
	s_nop 0
	s_nop 0
	s_nop 0
	s_nop 0
	s_nop 0
	s_nop 0
	s_nop 0
	s_nop 0
	s_nop 0
	s_nop 0
	s_nop 0
	s_nop 0
	s_nop 0
	s_nop 0
	s_waitcnt vmcnt(8)
	s_waitcnt lgkmcnt(0)
	s_barrier
	v_mfma_f32_16x16x32_bf16 v[114:117], v[130:133], v[220:223], v[114:117]
	v_mfma_f32_16x16x32_bf16 v[118:121], v[138:141], v[220:223], v[118:121]
	v_mfma_f32_16x16x32_bf16 v[110:113], v[130:133], v[228:231], v[110:113]
	v_mfma_f32_16x16x32_bf16 v[102:105], v[138:141], v[228:231], v[102:105]
	v_mfma_f32_16x16x32_bf16 v[94:97], v[130:133], v[236:239], v[94:97]
	v_mfma_f32_16x16x32_bf16 v[86:89], v[138:141], v[236:239], v[86:89]
	v_mfma_f32_16x16x32_bf16 v[78:81], v[130:133], v[244:247], v[78:81]
	v_mfma_f32_16x16x32_bf16 v[70:73], v[138:141], v[244:247], v[70:73]
	v_mfma_f32_16x16x32_bf16 v[114:117], v[134:137], v[224:227], v[114:117]
	v_mfma_f32_16x16x32_bf16 v[118:121], v[142:145], v[224:227], v[118:121]
	v_mfma_f32_16x16x32_bf16 v[110:113], v[134:137], v[232:235], v[110:113]
	v_mfma_f32_16x16x32_bf16 v[102:105], v[142:145], v[232:235], v[102:105]
	v_mfma_f32_16x16x32_bf16 v[94:97], v[134:137], v[240:243], v[94:97]
	v_mfma_f32_16x16x32_bf16 v[86:89], v[142:145], v[240:243], v[86:89]
	v_mfma_f32_16x16x32_bf16 v[78:81], v[134:137], v[248:251], v[78:81]
	v_mfma_f32_16x16x32_bf16 v[70:73], v[142:145], v[248:251], v[70:73]
	v_mfma_f32_16x16x32_bf16 v[126:129], v[146:149], v[220:223], v[126:129]
	v_mfma_f32_16x16x32_bf16 v[122:125], v[178:181], v[220:223], v[122:125]
	v_mfma_f32_16x16x32_bf16 v[106:109], v[146:149], v[228:231], v[106:109]
	v_mfma_f32_16x16x32_bf16 v[98:101], v[178:181], v[228:231], v[98:101]
	v_mfma_f32_16x16x32_bf16 v[90:93], v[146:149], v[236:239], v[90:93]
	v_mfma_f32_16x16x32_bf16 v[82:85], v[178:181], v[236:239], v[82:85]
	v_mfma_f32_16x16x32_bf16 v[74:77], v[146:149], v[244:247], v[74:77]
	v_mfma_f32_16x16x32_bf16 v[66:69], v[178:181], v[244:247], v[66:69]
	v_mfma_f32_16x16x32_bf16 v[126:129], v[150:153], v[224:227], v[126:129]
	v_mfma_f32_16x16x32_bf16 v[122:125], v[182:185], v[224:227], v[122:125]
	v_mfma_f32_16x16x32_bf16 v[106:109], v[150:153], v[232:235], v[106:109]
	v_mfma_f32_16x16x32_bf16 v[98:101], v[182:185], v[232:235], v[98:101]
	v_mfma_f32_16x16x32_bf16 v[90:93], v[150:153], v[240:243], v[90:93]
	v_mfma_f32_16x16x32_bf16 v[82:85], v[182:185], v[240:243], v[82:85]
	v_mfma_f32_16x16x32_bf16 v[74:77], v[150:153], v[248:251], v[74:77]
	v_mfma_f32_16x16x32_bf16 v[66:69], v[182:185], v[248:251], v[66:69]
	s_barrier
	s_add_i32 s69, s64, s49
	v_lshl_add_u64 v[252:253], s[44:45], 0, v[156:157]
	s_mov_b32 m0, s69
	ds_read_b128 v[220:223], v215 offset:16384
	ds_read_b128 v[224:227], v215 offset:17408
	ds_read_b128 v[228:231], v215 offset:18432
	ds_read_b128 v[232:235], v215 offset:19456
	ds_read_b128 v[236:239], v215 offset:20480
	ds_read_b128 v[240:243], v215 offset:21504
	ds_read_b128 v[244:247], v215 offset:22528
	ds_read_b128 v[248:251], v215 offset:23552
	global_load_lds_dwordx4 v[252:253], off
	s_add_i32 m0, s69, 0x2000
	s_add_u32 s70, s44, 0xb0000
	v_lshl_add_u64 v[172:173], s[44:45], 0, v[160:161]
	s_addc_u32 s71, s45, 0
	s_add_i32 s69, s65, s49
	global_load_lds_dwordx4 v[172:173], off
	v_lshl_add_u64 v[0:1], s[70:71], 0, v[156:157]
	s_mov_b32 m0, s69
	s_nop 0
	global_load_lds_dwordx4 v[0:1], off
	v_lshl_add_u64 v[0:1], s[70:71], 0, v[160:161]
	s_add_i32 m0, s69, 0x2000
	s_nop 0
	global_load_lds_dwordx4 v[0:1], off
	v_lshl_add_u64 v[0:1], s[46:47], 0, v[154:155]
	s_mov_b32 m0, s51
	s_nop 0
	global_load_lds_dwordx4 v[0:1], off
	v_lshl_add_u64 v[0:1], s[46:47], 0, v[158:159]
	s_mov_b32 m0, s52
	s_nop 0
	global_load_lds_dwordx4 v[0:1], off
	s_nop 0
	s_nop 0
	s_nop 0
	s_waitcnt vmcnt(8)
	s_waitcnt lgkmcnt(0)
	s_barrier
	v_mfma_f32_16x16x32_bf16 v[50:53], v[130:133], v[220:223], v[50:53]
	v_mfma_f32_16x16x32_bf16 v[54:57], v[138:141], v[220:223], v[54:57]
	v_mfma_f32_16x16x32_bf16 v[46:49], v[130:133], v[228:231], v[46:49]
	v_mfma_f32_16x16x32_bf16 v[38:41], v[138:141], v[228:231], v[38:41]
	v_mfma_f32_16x16x32_bf16 v[30:33], v[130:133], v[236:239], v[30:33]
	v_mfma_f32_16x16x32_bf16 v[22:25], v[138:141], v[236:239], v[22:25]
	v_mfma_f32_16x16x32_bf16 v[14:17], v[130:133], v[244:247], v[14:17]
	v_mfma_f32_16x16x32_bf16 v[6:9], v[138:141], v[244:247], v[6:9]
	v_mfma_f32_16x16x32_bf16 v[50:53], v[134:137], v[224:227], v[50:53]
	v_mfma_f32_16x16x32_bf16 v[54:57], v[142:145], v[224:227], v[54:57]
	v_mfma_f32_16x16x32_bf16 v[46:49], v[134:137], v[232:235], v[46:49]
	v_mfma_f32_16x16x32_bf16 v[38:41], v[142:145], v[232:235], v[38:41]
	v_mfma_f32_16x16x32_bf16 v[30:33], v[134:137], v[240:243], v[30:33]
	v_mfma_f32_16x16x32_bf16 v[22:25], v[142:145], v[240:243], v[22:25]
	v_mfma_f32_16x16x32_bf16 v[14:17], v[134:137], v[248:251], v[14:17]
	v_mfma_f32_16x16x32_bf16 v[6:9], v[142:145], v[248:251], v[6:9]
	v_mfma_f32_16x16x32_bf16 v[62:65], v[146:149], v[220:223], v[62:65]
	v_mfma_f32_16x16x32_bf16 v[58:61], v[178:181], v[220:223], v[58:61]
	v_mfma_f32_16x16x32_bf16 v[42:45], v[146:149], v[228:231], v[42:45]
	v_mfma_f32_16x16x32_bf16 v[34:37], v[178:181], v[228:231], v[34:37]
	v_mfma_f32_16x16x32_bf16 v[26:29], v[146:149], v[236:239], v[26:29]
	v_mfma_f32_16x16x32_bf16 v[18:21], v[178:181], v[236:239], v[18:21]
	v_mfma_f32_16x16x32_bf16 v[10:13], v[146:149], v[244:247], v[10:13]
	v_mfma_f32_16x16x32_bf16 v[0:3], v[178:181], v[244:247], v[2:5]
	v_mfma_f32_16x16x32_bf16 v[62:65], v[150:153], v[224:227], v[62:65]
	v_mfma_f32_16x16x32_bf16 v[58:61], v[182:185], v[224:227], v[58:61]
	v_mfma_f32_16x16x32_bf16 v[42:45], v[150:153], v[232:235], v[42:45]
	v_mfma_f32_16x16x32_bf16 v[34:37], v[182:185], v[232:235], v[34:37]
	v_mfma_f32_16x16x32_bf16 v[26:29], v[150:153], v[240:243], v[26:29]
	v_mfma_f32_16x16x32_bf16 v[18:21], v[182:185], v[240:243], v[18:21]
	v_mfma_f32_16x16x32_bf16 v[10:13], v[150:153], v[248:251], v[10:13]
	v_mfma_f32_16x16x32_bf16 v[0:3], v[182:185], v[248:251], v[0:3]
	s_barrier
	s_add_i32 s69, 0, 0x18000
	v_add_u32_e32 v4, s69, v187
	s_add_i32 s70, 0, 0x1c000
	ds_read_b128 v[130:133], v4
	ds_read_b128 v[134:137], v4 offset:1024
	ds_read_b128 v[138:141], v4 offset:2048
	ds_read_b128 v[142:145], v4 offset:3072
	v_add_u32_e32 v4, s70, v187
	ds_read_b128 v[146:149], v4
	ds_read_b128 v[150:153], v4 offset:1024
	ds_read_b128 v[178:181], v4 offset:2048
	ds_read_b128 v[182:185], v4 offset:3072
	s_add_u32 s46, s46, 0x4000
	s_addc_u32 s47, s47, 0
	s_mov_b32 m0, s53
	v_lshl_add_u64 v[4:5], s[46:47], 0, v[154:155]
	ds_read_b128 v[220:223], v215 offset:32768
	ds_read_b128 v[224:227], v215 offset:33792
	ds_read_b128 v[228:231], v215 offset:34816
	ds_read_b128 v[232:235], v215 offset:35840
	ds_read_b128 v[236:239], v215 offset:36864
	ds_read_b128 v[240:243], v215 offset:37888
	ds_read_b128 v[244:247], v215 offset:38912
	ds_read_b128 v[248:251], v215 offset:39936
	global_load_lds_dwordx4 v[4:5], off
	v_lshl_add_u64 v[4:5], s[46:47], 0, v[158:159]
	s_mov_b32 m0, s54
	s_nop 0
	global_load_lds_dwordx4 v[4:5], off
	s_nop 0
	s_nop 0
	s_nop 0
	s_nop 0
	s_nop 0
	s_nop 0
	s_nop 0
	s_nop 0
	s_waitcnt vmcnt(8)
	s_waitcnt lgkmcnt(0)
	s_barrier
	v_mfma_f32_16x16x32_bf16 v[114:117], v[130:133], v[220:223], v[114:117]
	v_mfma_f32_16x16x32_bf16 v[118:121], v[138:141], v[220:223], v[118:121]
	v_mfma_f32_16x16x32_bf16 v[110:113], v[130:133], v[228:231], v[110:113]
	v_mfma_f32_16x16x32_bf16 v[102:105], v[138:141], v[228:231], v[102:105]
	v_mfma_f32_16x16x32_bf16 v[94:97], v[130:133], v[236:239], v[94:97]
	v_mfma_f32_16x16x32_bf16 v[86:89], v[138:141], v[236:239], v[86:89]
	v_mfma_f32_16x16x32_bf16 v[78:81], v[130:133], v[244:247], v[78:81]
	v_mfma_f32_16x16x32_bf16 v[70:73], v[138:141], v[244:247], v[70:73]
	v_mfma_f32_16x16x32_bf16 v[114:117], v[134:137], v[224:227], v[114:117]
	v_mfma_f32_16x16x32_bf16 v[118:121], v[142:145], v[224:227], v[118:121]
	v_mfma_f32_16x16x32_bf16 v[110:113], v[134:137], v[232:235], v[110:113]
	v_mfma_f32_16x16x32_bf16 v[102:105], v[142:145], v[232:235], v[102:105]
	v_mfma_f32_16x16x32_bf16 v[94:97], v[134:137], v[240:243], v[94:97]
	v_mfma_f32_16x16x32_bf16 v[86:89], v[142:145], v[240:243], v[86:89]
	v_mfma_f32_16x16x32_bf16 v[78:81], v[134:137], v[248:251], v[78:81]
	v_mfma_f32_16x16x32_bf16 v[70:73], v[142:145], v[248:251], v[70:73]
	v_mfma_f32_16x16x32_bf16 v[126:129], v[146:149], v[220:223], v[126:129]
	v_mfma_f32_16x16x32_bf16 v[122:125], v[178:181], v[220:223], v[122:125]
	v_mfma_f32_16x16x32_bf16 v[106:109], v[146:149], v[228:231], v[106:109]
	v_mfma_f32_16x16x32_bf16 v[98:101], v[178:181], v[228:231], v[98:101]
	v_mfma_f32_16x16x32_bf16 v[90:93], v[146:149], v[236:239], v[90:93]
	v_mfma_f32_16x16x32_bf16 v[82:85], v[178:181], v[236:239], v[82:85]
	v_mfma_f32_16x16x32_bf16 v[74:77], v[146:149], v[244:247], v[74:77]
	v_mfma_f32_16x16x32_bf16 v[66:69], v[178:181], v[244:247], v[66:69]
	v_mfma_f32_16x16x32_bf16 v[126:129], v[150:153], v[224:227], v[126:129]
	v_mfma_f32_16x16x32_bf16 v[122:125], v[182:185], v[224:227], v[122:125]
	v_mfma_f32_16x16x32_bf16 v[106:109], v[150:153], v[232:235], v[106:109]
	v_mfma_f32_16x16x32_bf16 v[98:101], v[182:185], v[232:235], v[98:101]
	v_mfma_f32_16x16x32_bf16 v[90:93], v[150:153], v[240:243], v[90:93]
	v_mfma_f32_16x16x32_bf16 v[82:85], v[182:185], v[240:243], v[82:85]
	v_mfma_f32_16x16x32_bf16 v[74:77], v[150:153], v[248:251], v[74:77]
	v_mfma_f32_16x16x32_bf16 v[66:69], v[182:185], v[248:251], v[66:69]
	s_barrier
	s_add_i32 s46, s69, s49
	v_lshl_add_u64 v[4:5], v[252:253], 0, s[18:19]
	s_mov_b32 m0, s46
	ds_read_b128 v[220:223], v215 offset:49152
	ds_read_b128 v[224:227], v215 offset:50176
	ds_read_b128 v[228:231], v215 offset:51200
	ds_read_b128 v[232:235], v215 offset:52224
	ds_read_b128 v[236:239], v215 offset:53248
	ds_read_b128 v[240:243], v215 offset:54272
	ds_read_b128 v[244:247], v215 offset:55296
	ds_read_b128 v[248:251], v215 offset:56320
	global_load_lds_dwordx4 v[4:5], off
	s_add_i32 m0, s46, 0x2000
	s_add_u32 s44, s44, 0xb0080
	v_lshl_add_u64 v[4:5], v[172:173], 0, s[18:19]
	s_addc_u32 s45, s45, 0
	s_add_i32 s46, s70, s49
	global_load_lds_dwordx4 v[4:5], off
	v_lshl_add_u64 v[4:5], s[44:45], 0, v[156:157]
	s_mov_b32 m0, s46
	s_nop 0
	global_load_lds_dwordx4 v[4:5], off
	v_lshl_add_u64 v[4:5], s[44:45], 0, v[160:161]
	s_add_i32 m0, s46, 0x2000
	s_nop 0
	global_load_lds_dwordx4 v[4:5], off
	v_lshl_add_u64 v[4:5], s[42:43], 0, v[154:155]
	s_mov_b32 m0, s59
	s_nop 0
	global_load_lds_dwordx4 v[4:5], off
	v_lshl_add_u64 v[4:5], s[42:43], 0, v[158:159]
	s_mov_b32 m0, s60
	s_nop 0
	global_load_lds_dwordx4 v[4:5], off
	s_nop 0
	s_nop 0
	s_nop 0
	s_waitcnt vmcnt(8)
	s_waitcnt lgkmcnt(0)
	s_barrier
	v_mfma_f32_16x16x32_bf16 v[50:53], v[130:133], v[220:223], v[50:53]
	v_mfma_f32_16x16x32_bf16 v[54:57], v[138:141], v[220:223], v[54:57]
	v_mfma_f32_16x16x32_bf16 v[46:49], v[130:133], v[228:231], v[46:49]
	v_mfma_f32_16x16x32_bf16 v[38:41], v[138:141], v[228:231], v[38:41]
	v_mfma_f32_16x16x32_bf16 v[30:33], v[130:133], v[236:239], v[30:33]
	v_mfma_f32_16x16x32_bf16 v[22:25], v[138:141], v[236:239], v[22:25]
	v_mfma_f32_16x16x32_bf16 v[14:17], v[130:133], v[244:247], v[14:17]
	v_mfma_f32_16x16x32_bf16 v[4:7], v[138:141], v[244:247], v[6:9]
	v_mfma_f32_16x16x32_bf16 v[50:53], v[134:137], v[224:227], v[50:53]
	v_mfma_f32_16x16x32_bf16 v[54:57], v[142:145], v[224:227], v[54:57]
	v_mfma_f32_16x16x32_bf16 v[46:49], v[134:137], v[232:235], v[46:49]
	v_mfma_f32_16x16x32_bf16 v[38:41], v[142:145], v[232:235], v[38:41]
	v_mfma_f32_16x16x32_bf16 v[30:33], v[134:137], v[240:243], v[30:33]
	v_mfma_f32_16x16x32_bf16 v[22:25], v[142:145], v[240:243], v[22:25]
	v_mfma_f32_16x16x32_bf16 v[14:17], v[134:137], v[248:251], v[14:17]
	v_mfma_f32_16x16x32_bf16 v[6:9], v[142:145], v[248:251], v[4:7]
	v_mfma_f32_16x16x32_bf16 v[62:65], v[146:149], v[220:223], v[62:65]
	v_mfma_f32_16x16x32_bf16 v[58:61], v[178:181], v[220:223], v[58:61]
	v_mfma_f32_16x16x32_bf16 v[42:45], v[146:149], v[228:231], v[42:45]
	v_mfma_f32_16x16x32_bf16 v[34:37], v[178:181], v[228:231], v[34:37]
	v_mfma_f32_16x16x32_bf16 v[26:29], v[146:149], v[236:239], v[26:29]
	v_mfma_f32_16x16x32_bf16 v[18:21], v[178:181], v[236:239], v[18:21]
	v_mfma_f32_16x16x32_bf16 v[10:13], v[146:149], v[244:247], v[10:13]
	v_mfma_f32_16x16x32_bf16 v[0:3], v[178:181], v[244:247], v[0:3]
	v_mfma_f32_16x16x32_bf16 v[62:65], v[150:153], v[224:227], v[62:65]
	v_mfma_f32_16x16x32_bf16 v[58:61], v[182:185], v[224:227], v[58:61]
	v_mfma_f32_16x16x32_bf16 v[42:45], v[150:153], v[232:235], v[42:45]
	v_mfma_f32_16x16x32_bf16 v[34:37], v[182:185], v[232:235], v[34:37]
	v_mfma_f32_16x16x32_bf16 v[26:29], v[150:153], v[240:243], v[26:29]
	v_mfma_f32_16x16x32_bf16 v[18:21], v[182:185], v[240:243], v[18:21]
	v_mfma_f32_16x16x32_bf16 v[10:13], v[150:153], v[248:251], v[10:13]
	v_mfma_f32_16x16x32_bf16 v[2:5], v[182:185], v[248:251], v[0:3]
	s_barrier
	s_add_u32 s11, s11, 0x100
	s_addc_u32 s27, s27, 0
	s_add_u32 s36, s36, 0x800000
	s_addc_u32 s37, s37, 0
	s_cmp_ge_i32 s35, s58
	s_mov_b32 s42, s35
	s_cbranch_scc0 .LBB0_1009
	v_mov_b64_e32 v[234:235], v[174:175]
	s_and_b64 vcc, exec, s[22:23]
	s_cbranch_vccnz .LBB0_980
	s_branch .LBB0_981
